# scan block-end: state rescale multiplies fill the y-chain spacing slots instead of s_nop padding
# speedup vs baseline: 1.0012x; 1.0012x over previous
; #define LAS __attribute__((address_space(3)))
; DI unsigned pack2(float lo, float hi) { f32x2 v = {lo, hi}; return __builtin_bit_cast(unsigned, __builtin_convertvector(v, bf16x2_t)); }
; DI void scan_item(PP p, int l, int item, LAS unsigned char* lds) {
;     ...
;     for (int c = 0; c < NCH; ++c) {
;         if (wid >= 4) { if (c + 1 < NCH) { fill(c + 1); if (c + 2 < NCH) gl(c + 2); } }
;         else {
;             const LAS float* sp = buf + ((c & 1) * T) * 384;
;             f32x4 Ar0, Ar1, Aw0, Aw1, Ak0, Ak1, Aa0, Aa1, Ab0, Ab1; float Avv;
;             f32x4 Br0, Br1, Bw0, Bw1, Bk0, Bk1, Ba0, Ba1, Bb0, Bb1; float Bvv;
;             SC_LD(A, sp);
;             const ptrdiff_t ystep = dir ? -512 : 512;
;             u16* Yl = Yp + (size_t)steprow(b, dir, c * T) * 512 + (ptrdiff_t)ks * ystep;
; #pragma nounroll
;             for (int st = 0; st < T; st += 2) {
;                 SC_LD(B, sp + (st + 1) * 384);
;                 SC_STEP(A, st);
;                 if (st + 2 < T) SC_LD(A, sp + (st + 2) * 384);
;                 SC_STEP(B, st + 1);
;                 if ((st & 6) == 6) {
;                     const LAS float* rp = ypl + (ks * 68 - lane) + (lane & ~7);
;                     const f32x4 q0 = *(const LAS f32x4*)rp, q1 = *(const LAS f32x4*)(rp + 4);
;                     Yl[(ptrdiff_t)(st - 6) * ystep] = (u16)(pack2(((q0[0] + q0[1]) + (q0[2] + q0[3])) + ((q1[0] + q1[1]) + (q1[2] + q1[3])), 0.f) & 0xffffu);
;                 }
.Lscan_row_done:
	s_ashr_i32 s7, s6, 31
	s_lshl_b64 s[6:7], s[6:7], 10
	v_lshl_add_u64 v[118:119], v[80:81], 0, s[6:7]
	s_lshl_b32 s8, s41, 4
	s_mov_b32 s9, s31
	ds_read_b128 v[40:43], v154 offset:1536
	ds_read_b128 v[44:47], v154 offset:1552
	ds_read_b128 v[64:67], v154 offset:2304
	ds_read_b128 v[68:71], v154 offset:2320
	ds_read_b128 v[56:59], v154 offset:2048
	ds_read_b128 v[60:63], v154 offset:2064
	ds_read_b128 v[72:75], v154 offset:2560
	ds_read_b128 v[76:79], v154 offset:2576
	s_waitcnt lgkmcnt(8)
	v_pk_mul_f32 v[156:157], v[24:25], v[126:127]
	v_pk_mul_f32 v[90:91], v[28:29], v[122:123]
	v_pk_fma_f32 v[126:127], v[92:93], v[16:17], v[126:127] op_sel_hi:[0,1,1]
	v_pk_fma_f32 v[156:157], v[124:125], v[26:27], v[156:157]
	v_pk_fma_f32 v[90:91], v[120:121], v[30:31], v[90:91]
	v_pk_fma_f32 v[124:125], v[92:93], v[18:19], v[124:125] op_sel_hi:[0,1,1]
	v_pk_fma_f32 v[122:123], v[92:93], v[20:21], v[122:123] op_sel_hi:[0,1,1]
	v_pk_add_f32 v[156:157], v[156:157], v[90:91]
	v_pk_fma_f32 v[120:121], v[92:93], v[22:23], v[120:121] op_sel_hi:[0,1,1]
	v_add_f32_e32 v155, v156, v157
	s_nop 1
	v_add_f32_dpp v155, v155, v155 quad_perm:[1,0,3,2] row_mask:0xf bank_mask:0xf bound_ctrl:1
	s_nop 1
	v_add_f32_dpp v155, v155, v155 quad_perm:[2,3,0,1] row_mask:0xf bank_mask:0xf bound_ctrl:1
	s_nop 1
	v_add_f32_dpp v156, v155, v155 row_half_mirror row_mask:0xf bank_mask:0xf bound_ctrl:1
	v_pk_fma_f32 v[126:127], v[156:157], v[32:33], v[126:127] op_sel_hi:[0,1,1]
	v_pk_fma_f32 v[124:125], v[156:157], v[34:35], v[124:125] op_sel_hi:[0,1,1]
	v_pk_fma_f32 v[122:123], v[156:157], v[36:37], v[122:123] op_sel_hi:[0,1,1]
	v_pk_fma_f32 v[120:121], v[156:157], v[38:39], v[120:121] op_sel_hi:[0,1,1]
	ds_read_b128 v[24:27], v154 offset:3840
	ds_read_b128 v[28:31], v154 offset:3856
	ds_read_b128 v[16:19], v154 offset:3584
	ds_read_b128 v[20:23], v154 offset:3600
	ds_read_b128 v[32:35], v154 offset:4096
	ds_read_b128 v[36:39], v154 offset:4112
	ds_read2st64_b32 v[98:99], v153 offset0:17 offset1:23
	s_waitcnt lgkmcnt(7)
	v_pk_mul_f32 v[156:157], v[64:65], v[126:127]
	v_pk_mul_f32 v[90:91], v[68:69], v[122:123]
	v_pk_mul_f32 v[158:159], v[0:1], v[126:127]
	v_pk_fma_f32 v[156:157], v[124:125], v[66:67], v[156:157]
	v_pk_fma_f32 v[90:91], v[120:121], v[70:71], v[90:91]
	v_pk_fma_f32 v[158:159], v[124:125], v[2:3], v[158:159]
	v_pk_fma_f32 v[126:127], v[92:93], v[56:57], v[126:127] op_sel:[1,0,0] op_sel_hi:[1,1,1]
	v_pk_fma_f32 v[158:159], v[122:123], v[4:5], v[158:159]
	v_pk_fma_f32 v[124:125], v[92:93], v[58:59], v[124:125] op_sel:[1,0,0] op_sel_hi:[1,1,1]
	v_pk_add_f32 v[156:157], v[156:157], v[90:91]
	v_pk_fma_f32 v[158:159], v[120:121], v[6:7], v[158:159]
	v_add_f32_e32 v155, v156, v157
	v_pk_fma_f32 v[122:123], v[92:93], v[60:61], v[122:123] op_sel:[1,0,0] op_sel_hi:[1,1,1]
	v_pk_fma_f32 v[120:121], v[92:93], v[62:63], v[120:121] op_sel:[1,0,0] op_sel_hi:[1,1,1]
	ds_read_b128 v[0:3], v154 offset:3072
	ds_read_b128 v[4:7], v154 offset:3088
	v_add_f32_e32 v158, v158, v159
	v_add_f32_dpp v155, v155, v155 quad_perm:[1,0,3,2] row_mask:0xf bank_mask:0xf bound_ctrl:1
	s_mov_b32 s6, 0x1010101
	s_mov_b32 s7, 0x1010101
	v_add_f32_dpp v158, v158, v158 quad_perm:[1,0,3,2] row_mask:0xf bank_mask:0xf bound_ctrl:1
	v_add_f32_dpp v155, v155, v155 quad_perm:[2,3,0,1] row_mask:0xf bank_mask:0xf bound_ctrl:1
	s_nop 0
	v_add_f32_dpp v158, v158, v158 quad_perm:[2,3,0,1] row_mask:0xf bank_mask:0xf bound_ctrl:1
	v_add_f32_dpp v156, v155, v155 row_half_mirror row_mask:0xf bank_mask:0xf bound_ctrl:1
	v_pk_fma_f32 v[126:127], v[156:157], v[72:73], v[126:127] op_sel_hi:[0,1,1]
	v_pk_fma_f32 v[124:125], v[156:157], v[74:75], v[124:125] op_sel_hi:[0,1,1]
	v_add_f32_dpp v158, v158, v158 row_half_mirror row_mask:0xf bank_mask:0xf bound_ctrl:1
	v_pk_fma_f32 v[122:123], v[156:157], v[76:77], v[122:123] op_sel_hi:[0,1,1]
	v_pk_fma_f32 v[120:121], v[156:157], v[78:79], v[120:121] op_sel_hi:[0,1,1]
	v_cndmask_b32_e64 v94, v94, v158, s[6:7]
	ds_read_b128 v[64:67], v154 offset:5376
	ds_read_b128 v[68:71], v154 offset:5392
	ds_read_b128 v[56:59], v154 offset:5120
	ds_read_b128 v[60:63], v154 offset:5136
	ds_read_b128 v[72:75], v154 offset:5632
	ds_read_b128 v[76:79], v154 offset:5648
	s_waitcnt lgkmcnt(6)
	v_pk_mul_f32 v[156:157], v[24:25], v[126:127]
	v_pk_mul_f32 v[90:91], v[28:29], v[122:123]
	v_pk_mul_f32 v[158:159], v[40:41], v[126:127]
	v_pk_fma_f32 v[156:157], v[124:125], v[26:27], v[156:157]
	v_pk_fma_f32 v[90:91], v[120:121], v[30:31], v[90:91]
	v_pk_fma_f32 v[158:159], v[124:125], v[42:43], v[158:159]
	v_pk_fma_f32 v[126:127], v[98:99], v[16:17], v[126:127] op_sel_hi:[0,1,1]
	v_pk_fma_f32 v[158:159], v[122:123], v[44:45], v[158:159]
	v_pk_fma_f32 v[124:125], v[98:99], v[18:19], v[124:125] op_sel_hi:[0,1,1]
	v_pk_add_f32 v[156:157], v[156:157], v[90:91]
	v_pk_fma_f32 v[158:159], v[120:121], v[46:47], v[158:159]
	v_add_f32_e32 v155, v156, v157
	v_pk_fma_f32 v[122:123], v[98:99], v[20:21], v[122:123] op_sel_hi:[0,1,1]
	v_pk_fma_f32 v[120:121], v[98:99], v[22:23], v[120:121] op_sel_hi:[0,1,1]
	ds_read_b128 v[40:43], v154 offset:4608
	ds_read_b128 v[44:47], v154 offset:4624
	v_add_f32_e32 v158, v158, v159
	v_add_f32_dpp v155, v155, v155 quad_perm:[1,0,3,2] row_mask:0xf bank_mask:0xf bound_ctrl:1
	s_mov_b32 s6, 0x2020202
	s_mov_b32 s7, 0x2020202
	v_add_f32_dpp v158, v158, v158 quad_perm:[1,0,3,2] row_mask:0xf bank_mask:0xf bound_ctrl:1
	v_add_f32_dpp v155, v155, v155 quad_perm:[2,3,0,1] row_mask:0xf bank_mask:0xf bound_ctrl:1
	s_nop 0
	v_add_f32_dpp v158, v158, v158 quad_perm:[2,3,0,1] row_mask:0xf bank_mask:0xf bound_ctrl:1
	v_add_f32_dpp v156, v155, v155 row_half_mirror row_mask:0xf bank_mask:0xf bound_ctrl:1
	v_pk_fma_f32 v[126:127], v[156:157], v[32:33], v[126:127] op_sel_hi:[0,1,1]
	v_pk_fma_f32 v[124:125], v[156:157], v[34:35], v[124:125] op_sel_hi:[0,1,1]
	v_add_f32_dpp v158, v158, v158 row_half_mirror row_mask:0xf bank_mask:0xf bound_ctrl:1
	v_pk_fma_f32 v[122:123], v[156:157], v[36:37], v[122:123] op_sel_hi:[0,1,1]
	v_pk_fma_f32 v[120:121], v[156:157], v[38:39], v[120:121] op_sel_hi:[0,1,1]
	v_cndmask_b32_e64 v94, v94, v158, s[6:7]
	ds_read_b128 v[24:27], v154 offset:6912
	ds_read_b128 v[28:31], v154 offset:6928
	ds_read_b128 v[16:19], v154 offset:6656
	ds_read_b128 v[20:23], v154 offset:6672
	ds_read_b128 v[32:35], v154 offset:7168
	ds_read_b128 v[36:39], v154 offset:7184
	ds_read2st64_b32 v[92:93], v153 offset0:29 offset1:35
	s_waitcnt lgkmcnt(7)
; #define LAS __attribute__((address_space(3)))
; DI unsigned pack2(float lo, float hi) { f32x2 v = {lo, hi}; return __builtin_bit_cast(unsigned, __builtin_convertvector(v, bf16x2_t)); }
; DI void scan_item(PP p, int l, int item, LAS unsigned char* lds) {
;     ...
;     for (int c = 0; c < NCH; ++c) {
;         if (wid >= 4) { if (c + 1 < NCH) { fill(c + 1); if (c + 2 < NCH) gl(c + 2); } }
;         else {
;             const LAS float* sp = buf + ((c & 1) * T) * 384;
;             f32x4 Ar0, Ar1, Aw0, Aw1, Ak0, Ak1, Aa0, Aa1, Ab0, Ab1; float Avv;
;             f32x4 Br0, Br1, Bw0, Bw1, Bk0, Bk1, Ba0, Ba1, Bb0, Bb1; float Bvv;
;             SC_LD(A, sp);
;             const ptrdiff_t ystep = dir ? -512 : 512;
;             u16* Yl = Yp + (size_t)steprow(b, dir, c * T) * 512 + (ptrdiff_t)ks * ystep;
; #pragma nounroll
;             for (int st = 0; st < T; st += 2) {
;                 SC_LD(B, sp + (st + 1) * 384);
;                 SC_STEP(A, st);
;                 if (st + 2 < T) SC_LD(A, sp + (st + 2) * 384);
;                 SC_STEP(B, st + 1);
;                 if ((st & 6) == 6) {
;                     const LAS float* rp = ypl + (ks * 68 - lane) + (lane & ~7);
;                     const f32x4 q0 = *(const LAS f32x4*)rp, q1 = *(const LAS f32x4*)(rp + 4);
;                     Yl[(ptrdiff_t)(st - 6) * ystep] = (u16)(pack2(((q0[0] + q0[1]) + (q0[2] + q0[3])) + ((q1[0] + q1[1]) + (q1[2] + q1[3])), 0.f) & 0xffffu);
;                 }
	v_pk_mul_f32 v[156:157], v[64:65], v[126:127]
	v_pk_mul_f32 v[90:91], v[68:69], v[122:123]
	v_pk_mul_f32 v[158:159], v[0:1], v[126:127]
	v_pk_fma_f32 v[156:157], v[124:125], v[66:67], v[156:157]
	v_pk_fma_f32 v[90:91], v[120:121], v[70:71], v[90:91]
	v_pk_fma_f32 v[158:159], v[124:125], v[2:3], v[158:159]
	v_pk_fma_f32 v[126:127], v[98:99], v[56:57], v[126:127] op_sel:[1,0,0] op_sel_hi:[1,1,1]
	v_pk_fma_f32 v[158:159], v[122:123], v[4:5], v[158:159]
	v_pk_fma_f32 v[124:125], v[98:99], v[58:59], v[124:125] op_sel:[1,0,0] op_sel_hi:[1,1,1]
	v_pk_add_f32 v[156:157], v[156:157], v[90:91]
	v_pk_fma_f32 v[158:159], v[120:121], v[6:7], v[158:159]
	v_add_f32_e32 v155, v156, v157
	v_pk_fma_f32 v[122:123], v[98:99], v[60:61], v[122:123] op_sel:[1,0,0] op_sel_hi:[1,1,1]
	v_pk_fma_f32 v[120:121], v[98:99], v[62:63], v[120:121] op_sel:[1,0,0] op_sel_hi:[1,1,1]
	ds_read_b128 v[0:3], v154 offset:6144
	ds_read_b128 v[4:7], v154 offset:6160
	v_add_f32_e32 v158, v158, v159
	v_add_f32_dpp v155, v155, v155 quad_perm:[1,0,3,2] row_mask:0xf bank_mask:0xf bound_ctrl:1
	s_mov_b32 s6, 0x4040404
	s_mov_b32 s7, 0x4040404
	v_add_f32_dpp v158, v158, v158 quad_perm:[1,0,3,2] row_mask:0xf bank_mask:0xf bound_ctrl:1
	v_add_f32_dpp v155, v155, v155 quad_perm:[2,3,0,1] row_mask:0xf bank_mask:0xf bound_ctrl:1
	s_nop 0
	v_add_f32_dpp v158, v158, v158 quad_perm:[2,3,0,1] row_mask:0xf bank_mask:0xf bound_ctrl:1
	v_add_f32_dpp v156, v155, v155 row_half_mirror row_mask:0xf bank_mask:0xf bound_ctrl:1
	v_pk_fma_f32 v[126:127], v[156:157], v[72:73], v[126:127] op_sel_hi:[0,1,1]
	v_pk_fma_f32 v[124:125], v[156:157], v[74:75], v[124:125] op_sel_hi:[0,1,1]
	v_add_f32_dpp v158, v158, v158 row_half_mirror row_mask:0xf bank_mask:0xf bound_ctrl:1
	v_pk_fma_f32 v[122:123], v[156:157], v[76:77], v[122:123] op_sel_hi:[0,1,1]
	v_pk_fma_f32 v[120:121], v[156:157], v[78:79], v[120:121] op_sel_hi:[0,1,1]
	v_cndmask_b32_e64 v94, v94, v158, s[6:7]
	ds_read_b128 v[64:67], v154 offset:8448
	ds_read_b128 v[68:71], v154 offset:8464
	ds_read_b128 v[56:59], v154 offset:8192
	ds_read_b128 v[60:63], v154 offset:8208
	ds_read_b128 v[72:75], v154 offset:8704
	ds_read_b128 v[76:79], v154 offset:8720
	s_waitcnt lgkmcnt(6)
	v_pk_mul_f32 v[156:157], v[24:25], v[126:127]
	v_pk_mul_f32 v[90:91], v[28:29], v[122:123]
	v_pk_mul_f32 v[158:159], v[40:41], v[126:127]
	v_pk_fma_f32 v[156:157], v[124:125], v[26:27], v[156:157]
	v_pk_fma_f32 v[90:91], v[120:121], v[30:31], v[90:91]
	v_pk_fma_f32 v[158:159], v[124:125], v[42:43], v[158:159]
	v_pk_fma_f32 v[126:127], v[92:93], v[16:17], v[126:127] op_sel_hi:[0,1,1]
	v_pk_fma_f32 v[158:159], v[122:123], v[44:45], v[158:159]
	v_pk_fma_f32 v[124:125], v[92:93], v[18:19], v[124:125] op_sel_hi:[0,1,1]
	v_pk_add_f32 v[156:157], v[156:157], v[90:91]
	v_pk_fma_f32 v[158:159], v[120:121], v[46:47], v[158:159]
	v_add_f32_e32 v155, v156, v157
	v_pk_fma_f32 v[122:123], v[92:93], v[20:21], v[122:123] op_sel_hi:[0,1,1]
	v_pk_fma_f32 v[120:121], v[92:93], v[22:23], v[120:121] op_sel_hi:[0,1,1]
	ds_read_b128 v[40:43], v154 offset:7680
	ds_read_b128 v[44:47], v154 offset:7696
	v_add_f32_e32 v158, v158, v159
	v_add_f32_dpp v155, v155, v155 quad_perm:[1,0,3,2] row_mask:0xf bank_mask:0xf bound_ctrl:1
	s_mov_b32 s6, 0x8080808
	s_mov_b32 s7, 0x8080808
	v_add_f32_dpp v158, v158, v158 quad_perm:[1,0,3,2] row_mask:0xf bank_mask:0xf bound_ctrl:1
	v_add_f32_dpp v155, v155, v155 quad_perm:[2,3,0,1] row_mask:0xf bank_mask:0xf bound_ctrl:1
	s_nop 0
	v_add_f32_dpp v158, v158, v158 quad_perm:[2,3,0,1] row_mask:0xf bank_mask:0xf bound_ctrl:1
	v_add_f32_dpp v156, v155, v155 row_half_mirror row_mask:0xf bank_mask:0xf bound_ctrl:1
	v_pk_fma_f32 v[126:127], v[156:157], v[32:33], v[126:127] op_sel_hi:[0,1,1]
	v_pk_fma_f32 v[124:125], v[156:157], v[34:35], v[124:125] op_sel_hi:[0,1,1]
	v_add_f32_dpp v158, v158, v158 row_half_mirror row_mask:0xf bank_mask:0xf bound_ctrl:1
	v_pk_fma_f32 v[122:123], v[156:157], v[36:37], v[122:123] op_sel_hi:[0,1,1]
	v_pk_fma_f32 v[120:121], v[156:157], v[38:39], v[120:121] op_sel_hi:[0,1,1]
	v_cndmask_b32_e64 v94, v94, v158, s[6:7]
	ds_read_b128 v[24:27], v154 offset:9984
	ds_read_b128 v[28:31], v154 offset:10000
	ds_read_b128 v[16:19], v154 offset:9728
	ds_read_b128 v[20:23], v154 offset:9744
	ds_read_b128 v[32:35], v154 offset:10240
	ds_read_b128 v[36:39], v154 offset:10256
	ds_read2st64_b32 v[98:99], v153 offset0:41 offset1:47
	s_waitcnt lgkmcnt(7)
	v_pk_mul_f32 v[156:157], v[64:65], v[126:127]
	v_pk_mul_f32 v[90:91], v[68:69], v[122:123]
	v_pk_mul_f32 v[158:159], v[0:1], v[126:127]
	v_pk_fma_f32 v[156:157], v[124:125], v[66:67], v[156:157]
	v_pk_fma_f32 v[90:91], v[120:121], v[70:71], v[90:91]
	v_pk_fma_f32 v[158:159], v[124:125], v[2:3], v[158:159]
	v_pk_fma_f32 v[126:127], v[92:93], v[56:57], v[126:127] op_sel:[1,0,0] op_sel_hi:[1,1,1]
	v_pk_fma_f32 v[158:159], v[122:123], v[4:5], v[158:159]
	v_pk_fma_f32 v[124:125], v[92:93], v[58:59], v[124:125] op_sel:[1,0,0] op_sel_hi:[1,1,1]
	v_pk_add_f32 v[156:157], v[156:157], v[90:91]
	v_pk_fma_f32 v[158:159], v[120:121], v[6:7], v[158:159]
	v_add_f32_e32 v155, v156, v157
	v_pk_fma_f32 v[122:123], v[92:93], v[60:61], v[122:123] op_sel:[1,0,0] op_sel_hi:[1,1,1]
	v_pk_fma_f32 v[120:121], v[92:93], v[62:63], v[120:121] op_sel:[1,0,0] op_sel_hi:[1,1,1]
	ds_read_b128 v[0:3], v154 offset:9216
	ds_read_b128 v[4:7], v154 offset:9232
	v_add_f32_e32 v158, v158, v159
	v_add_f32_dpp v155, v155, v155 quad_perm:[1,0,3,2] row_mask:0xf bank_mask:0xf bound_ctrl:1
	s_mov_b32 s6, 0x10101010
	s_mov_b32 s7, 0x10101010
	v_add_f32_dpp v158, v158, v158 quad_perm:[1,0,3,2] row_mask:0xf bank_mask:0xf bound_ctrl:1
	v_add_f32_dpp v155, v155, v155 quad_perm:[2,3,0,1] row_mask:0xf bank_mask:0xf bound_ctrl:1
	s_nop 0
	v_add_f32_dpp v158, v158, v158 quad_perm:[2,3,0,1] row_mask:0xf bank_mask:0xf bound_ctrl:1
	v_add_f32_dpp v156, v155, v155 row_half_mirror row_mask:0xf bank_mask:0xf bound_ctrl:1
	v_pk_fma_f32 v[126:127], v[156:157], v[72:73], v[126:127] op_sel_hi:[0,1,1]
	v_pk_fma_f32 v[124:125], v[156:157], v[74:75], v[124:125] op_sel_hi:[0,1,1]
	v_add_f32_dpp v158, v158, v158 row_half_mirror row_mask:0xf bank_mask:0xf bound_ctrl:1
	v_pk_fma_f32 v[122:123], v[156:157], v[76:77], v[122:123] op_sel_hi:[0,1,1]
	v_pk_fma_f32 v[120:121], v[156:157], v[78:79], v[120:121] op_sel_hi:[0,1,1]
	v_cndmask_b32_e64 v94, v94, v158, s[6:7]
	ds_read_b128 v[64:67], v154 offset:11520
	ds_read_b128 v[68:71], v154 offset:11536
	ds_read_b128 v[56:59], v154 offset:11264
	ds_read_b128 v[60:63], v154 offset:11280
	ds_read_b128 v[72:75], v154 offset:11776
	ds_read_b128 v[76:79], v154 offset:11792
	ds_read_b128 v[48:51], v154 offset:11008
	ds_read_b128 v[52:55], v154 offset:11024
	s_waitcnt lgkmcnt(8)
; #define LAS __attribute__((address_space(3)))
; DI unsigned pack2(float lo, float hi) { f32x2 v = {lo, hi}; return __builtin_bit_cast(unsigned, __builtin_convertvector(v, bf16x2_t)); }
; DI void scan_item(PP p, int l, int item, LAS unsigned char* lds) {
;     ...
;     for (int c = 0; c < NCH; ++c) {
;         if (wid >= 4) { if (c + 1 < NCH) { fill(c + 1); if (c + 2 < NCH) gl(c + 2); } }
;         else {
;             const LAS float* sp = buf + ((c & 1) * T) * 384;
;             f32x4 Ar0, Ar1, Aw0, Aw1, Ak0, Ak1, Aa0, Aa1, Ab0, Ab1; float Avv;
;             f32x4 Br0, Br1, Bw0, Bw1, Bk0, Bk1, Ba0, Ba1, Bb0, Bb1; float Bvv;
;             SC_LD(A, sp);
;             const ptrdiff_t ystep = dir ? -512 : 512;
;             u16* Yl = Yp + (size_t)steprow(b, dir, c * T) * 512 + (ptrdiff_t)ks * ystep;
; #pragma nounroll
;             for (int st = 0; st < T; st += 2) {
;                 SC_LD(B, sp + (st + 1) * 384);
;                 SC_STEP(A, st);
;                 if (st + 2 < T) SC_LD(A, sp + (st + 2) * 384);
;                 SC_STEP(B, st + 1);
;                 if ((st & 6) == 6) {
;                     const LAS float* rp = ypl + (ks * 68 - lane) + (lane & ~7);
;                     const f32x4 q0 = *(const LAS f32x4*)rp, q1 = *(const LAS f32x4*)(rp + 4);
;                     Yl[(ptrdiff_t)(st - 6) * ystep] = (u16)(pack2(((q0[0] + q0[1]) + (q0[2] + q0[3])) + ((q1[0] + q1[1]) + (q1[2] + q1[3])), 0.f) & 0xffffu);
;                 }
	v_pk_mul_f32 v[156:157], v[24:25], v[126:127]
	v_pk_mul_f32 v[90:91], v[28:29], v[122:123]
	v_pk_mul_f32 v[158:159], v[40:41], v[126:127]
	v_pk_fma_f32 v[156:157], v[124:125], v[26:27], v[156:157]
	v_pk_fma_f32 v[90:91], v[120:121], v[30:31], v[90:91]
	v_pk_fma_f32 v[158:159], v[124:125], v[42:43], v[158:159]
	v_pk_fma_f32 v[126:127], v[98:99], v[16:17], v[126:127] op_sel_hi:[0,1,1]
	v_pk_fma_f32 v[158:159], v[122:123], v[44:45], v[158:159]
	v_pk_fma_f32 v[124:125], v[98:99], v[18:19], v[124:125] op_sel_hi:[0,1,1]
	v_pk_add_f32 v[156:157], v[156:157], v[90:91]
	v_pk_fma_f32 v[158:159], v[120:121], v[46:47], v[158:159]
	v_add_f32_e32 v155, v156, v157
	v_pk_fma_f32 v[122:123], v[98:99], v[20:21], v[122:123] op_sel_hi:[0,1,1]
	v_pk_fma_f32 v[120:121], v[98:99], v[22:23], v[120:121] op_sel_hi:[0,1,1]
	ds_read_b128 v[40:43], v154 offset:10752
	ds_read_b128 v[44:47], v154 offset:10768
	v_add_f32_e32 v158, v158, v159
	v_add_f32_dpp v155, v155, v155 quad_perm:[1,0,3,2] row_mask:0xf bank_mask:0xf bound_ctrl:1
	s_mov_b32 s6, 0x20202020
	s_mov_b32 s7, 0x20202020
	v_add_f32_dpp v158, v158, v158 quad_perm:[1,0,3,2] row_mask:0xf bank_mask:0xf bound_ctrl:1
	v_add_f32_dpp v155, v155, v155 quad_perm:[2,3,0,1] row_mask:0xf bank_mask:0xf bound_ctrl:1
	s_nop 0
	v_add_f32_dpp v158, v158, v158 quad_perm:[2,3,0,1] row_mask:0xf bank_mask:0xf bound_ctrl:1
	v_add_f32_dpp v156, v155, v155 row_half_mirror row_mask:0xf bank_mask:0xf bound_ctrl:1
	v_pk_fma_f32 v[126:127], v[156:157], v[32:33], v[126:127] op_sel_hi:[0,1,1]
	v_pk_fma_f32 v[124:125], v[156:157], v[34:35], v[124:125] op_sel_hi:[0,1,1]
	v_add_f32_dpp v158, v158, v158 row_half_mirror row_mask:0xf bank_mask:0xf bound_ctrl:1
	v_pk_fma_f32 v[122:123], v[156:157], v[36:37], v[122:123] op_sel_hi:[0,1,1]
	v_pk_fma_f32 v[120:121], v[156:157], v[38:39], v[120:121] op_sel_hi:[0,1,1]
	v_cndmask_b32_e64 v94, v94, v158, s[6:7]
	ds_read_b128 v[24:27], v154 offset:13056
	ds_read_b128 v[28:31], v154 offset:13072
	ds_read_b128 v[16:19], v154 offset:12800
	ds_read_b128 v[20:23], v154 offset:12816
	ds_read_b128 v[32:35], v154 offset:13312
	ds_read_b128 v[36:39], v154 offset:13328
	ds_read2st64_b32 v[92:93], v153 offset0:53 offset1:59
	s_waitcnt lgkmcnt(7)
	v_pk_mul_f32 v[156:157], v[64:65], v[126:127]
	v_pk_mul_f32 v[90:91], v[68:69], v[122:123]
	v_pk_mul_f32 v[158:159], v[0:1], v[126:127]
	v_pk_fma_f32 v[156:157], v[124:125], v[66:67], v[156:157]
	v_pk_fma_f32 v[90:91], v[120:121], v[70:71], v[90:91]
	v_pk_fma_f32 v[158:159], v[124:125], v[2:3], v[158:159]
	v_pk_fma_f32 v[126:127], v[98:99], v[56:57], v[126:127] op_sel:[1,0,0] op_sel_hi:[1,1,1]
	v_pk_fma_f32 v[158:159], v[122:123], v[4:5], v[158:159]
	v_pk_fma_f32 v[124:125], v[98:99], v[58:59], v[124:125] op_sel:[1,0,0] op_sel_hi:[1,1,1]
	v_pk_add_f32 v[156:157], v[156:157], v[90:91]
	v_pk_fma_f32 v[158:159], v[120:121], v[6:7], v[158:159]
	v_add_f32_e32 v155, v156, v157
	v_pk_fma_f32 v[122:123], v[98:99], v[60:61], v[122:123] op_sel:[1,0,0] op_sel_hi:[1,1,1]
	v_pk_fma_f32 v[120:121], v[98:99], v[62:63], v[120:121] op_sel:[1,0,0] op_sel_hi:[1,1,1]
	ds_read_b128 v[0:3], v154 offset:12288
	ds_read_b128 v[4:7], v154 offset:12304
	v_add_f32_e32 v158, v158, v159
	v_add_f32_dpp v155, v155, v155 quad_perm:[1,0,3,2] row_mask:0xf bank_mask:0xf bound_ctrl:1
	s_mov_b32 s6, 0x40404040
	s_mov_b32 s7, 0x40404040
	v_add_f32_dpp v158, v158, v158 quad_perm:[1,0,3,2] row_mask:0xf bank_mask:0xf bound_ctrl:1
	v_add_f32_dpp v155, v155, v155 quad_perm:[2,3,0,1] row_mask:0xf bank_mask:0xf bound_ctrl:1
	s_nop 0
	v_add_f32_dpp v158, v158, v158 quad_perm:[2,3,0,1] row_mask:0xf bank_mask:0xf bound_ctrl:1
	v_add_f32_dpp v156, v155, v155 row_half_mirror row_mask:0xf bank_mask:0xf bound_ctrl:1
	v_pk_fma_f32 v[126:127], v[156:157], v[72:73], v[126:127] op_sel_hi:[0,1,1]
	v_pk_fma_f32 v[124:125], v[156:157], v[74:75], v[124:125] op_sel_hi:[0,1,1]
	v_add_f32_dpp v158, v158, v158 row_half_mirror row_mask:0xf bank_mask:0xf bound_ctrl:1
	v_pk_fma_f32 v[122:123], v[156:157], v[76:77], v[122:123] op_sel_hi:[0,1,1]
	v_pk_fma_f32 v[120:121], v[156:157], v[78:79], v[120:121] op_sel_hi:[0,1,1]
	v_cndmask_b32_e64 v94, v94, v158, s[6:7]
	v_pk_mul_f32 v[158:159], v[40:41], v[126:127]
	v_pk_mul_f32 v[126:127], v[48:49], v[126:127]
	v_pk_fma_f32 v[158:159], v[124:125], v[42:43], v[158:159]
	v_pk_mul_f32 v[124:125], v[50:51], v[124:125]
	v_pk_fma_f32 v[158:159], v[122:123], v[44:45], v[158:159]
	v_pk_mul_f32 v[122:123], v[52:53], v[122:123]
	v_pk_fma_f32 v[158:159], v[120:121], v[46:47], v[158:159]
	v_pk_mul_f32 v[120:121], v[54:55], v[120:121]
	v_add_f32_e32 v158, v158, v159
	s_mov_b32 s6, 0x80808080
	s_mov_b32 s7, 0x80808080
	v_add_f32_dpp v158, v158, v158 quad_perm:[1,0,3,2] row_mask:0xf bank_mask:0xf bound_ctrl:1
	s_nop 1
	v_add_f32_dpp v158, v158, v158 quad_perm:[2,3,0,1] row_mask:0xf bank_mask:0xf bound_ctrl:1
	s_nop 1
	v_add_f32_dpp v158, v158, v158 row_half_mirror row_mask:0xf bank_mask:0xf bound_ctrl:1
	v_cndmask_b32_e64 v94, v94, v158, s[6:7]
	ds_read_b128 v[40:43], v154 offset:13824
	ds_read_b128 v[44:47], v154 offset:13840
	ds_read_b128 v[64:67], v154 offset:14592
	ds_read_b128 v[68:71], v154 offset:14608
	ds_read_b128 v[56:59], v154 offset:14336
	ds_read_b128 v[60:63], v154 offset:14352
	ds_read_b128 v[72:75], v154 offset:14848
	ds_read_b128 v[76:79], v154 offset:14864
	s_waitcnt lgkmcnt(8)
; #define LAS __attribute__((address_space(3)))
; DI unsigned pack2(float lo, float hi) { f32x2 v = {lo, hi}; return __builtin_bit_cast(unsigned, __builtin_convertvector(v, bf16x2_t)); }
; DI void scan_item(PP p, int l, int item, LAS unsigned char* lds) {
;     ...
;     for (int c = 0; c < NCH; ++c) {
;         if (wid >= 4) { if (c + 1 < NCH) { fill(c + 1); if (c + 2 < NCH) gl(c + 2); } }
;         else {
;             const LAS float* sp = buf + ((c & 1) * T) * 384;
;             f32x4 Ar0, Ar1, Aw0, Aw1, Ak0, Ak1, Aa0, Aa1, Ab0, Ab1; float Avv;
;             f32x4 Br0, Br1, Bw0, Bw1, Bk0, Bk1, Ba0, Ba1, Bb0, Bb1; float Bvv;
;             SC_LD(A, sp);
;             const ptrdiff_t ystep = dir ? -512 : 512;
;             u16* Yl = Yp + (size_t)steprow(b, dir, c * T) * 512 + (ptrdiff_t)ks * ystep;
; #pragma nounroll
;             for (int st = 0; st < T; st += 2) {
;                 SC_LD(B, sp + (st + 1) * 384);
;                 SC_STEP(A, st);
;                 if (st + 2 < T) SC_LD(A, sp + (st + 2) * 384);
;                 SC_STEP(B, st + 1);
;                 if ((st & 6) == 6) {
;                     const LAS float* rp = ypl + (ks * 68 - lane) + (lane & ~7);
;                     const f32x4 q0 = *(const LAS f32x4*)rp, q1 = *(const LAS f32x4*)(rp + 4);
;                     Yl[(ptrdiff_t)(st - 6) * ystep] = (u16)(pack2(((q0[0] + q0[1]) + (q0[2] + q0[3])) + ((q1[0] + q1[1]) + (q1[2] + q1[3])), 0.f) & 0xffffu);
;                 }
	v_pk_mul_f32 v[156:157], v[24:25], v[126:127]
	v_pk_mul_f32 v[90:91], v[28:29], v[122:123]
	v_pk_fma_f32 v[126:127], v[92:93], v[16:17], v[126:127] op_sel_hi:[0,1,1]
	v_pk_fma_f32 v[156:157], v[124:125], v[26:27], v[156:157]
	v_pk_fma_f32 v[90:91], v[120:121], v[30:31], v[90:91]
	v_pk_fma_f32 v[124:125], v[92:93], v[18:19], v[124:125] op_sel_hi:[0,1,1]
	v_pk_fma_f32 v[122:123], v[92:93], v[20:21], v[122:123] op_sel_hi:[0,1,1]
	v_pk_add_f32 v[156:157], v[156:157], v[90:91]
	v_pk_fma_f32 v[120:121], v[92:93], v[22:23], v[120:121] op_sel_hi:[0,1,1]
	v_add_f32_e32 v155, v156, v157
	s_nop 1
	v_add_f32_dpp v155, v155, v155 quad_perm:[1,0,3,2] row_mask:0xf bank_mask:0xf bound_ctrl:1
	s_nop 1
	v_add_f32_dpp v155, v155, v155 quad_perm:[2,3,0,1] row_mask:0xf bank_mask:0xf bound_ctrl:1
	s_nop 1
	v_add_f32_dpp v156, v155, v155 row_half_mirror row_mask:0xf bank_mask:0xf bound_ctrl:1
	v_pk_fma_f32 v[126:127], v[156:157], v[32:33], v[126:127] op_sel_hi:[0,1,1]
	v_pk_fma_f32 v[124:125], v[156:157], v[34:35], v[124:125] op_sel_hi:[0,1,1]
	v_pk_fma_f32 v[122:123], v[156:157], v[36:37], v[122:123] op_sel_hi:[0,1,1]
	v_pk_fma_f32 v[120:121], v[156:157], v[38:39], v[120:121] op_sel_hi:[0,1,1]
	v_cvt_pk_bf16_f32 v82, v94, v94
	global_store_short v[118:119], v82, off
	v_lshl_add_u64 v[118:119], s[8:9], 0, v[118:119]
	ds_read_b128 v[24:27], v154 offset:16128
	ds_read_b128 v[28:31], v154 offset:16144
	ds_read_b128 v[16:19], v154 offset:15872
	ds_read_b128 v[20:23], v154 offset:15888
	ds_read_b128 v[32:35], v154 offset:16384
	ds_read_b128 v[36:39], v154 offset:16400
	ds_read2st64_b32 v[98:99], v153 offset0:65 offset1:71
	s_waitcnt lgkmcnt(7)
	v_pk_mul_f32 v[156:157], v[64:65], v[126:127]
	v_pk_mul_f32 v[90:91], v[68:69], v[122:123]
	v_pk_mul_f32 v[158:159], v[0:1], v[126:127]
	v_pk_fma_f32 v[156:157], v[124:125], v[66:67], v[156:157]
	v_pk_fma_f32 v[90:91], v[120:121], v[70:71], v[90:91]
	v_pk_fma_f32 v[158:159], v[124:125], v[2:3], v[158:159]
	v_pk_fma_f32 v[126:127], v[92:93], v[56:57], v[126:127] op_sel:[1,0,0] op_sel_hi:[1,1,1]
	v_pk_fma_f32 v[158:159], v[122:123], v[4:5], v[158:159]
	v_pk_fma_f32 v[124:125], v[92:93], v[58:59], v[124:125] op_sel:[1,0,0] op_sel_hi:[1,1,1]
	v_pk_add_f32 v[156:157], v[156:157], v[90:91]
	v_pk_fma_f32 v[158:159], v[120:121], v[6:7], v[158:159]
	v_add_f32_e32 v155, v156, v157
	v_pk_fma_f32 v[122:123], v[92:93], v[60:61], v[122:123] op_sel:[1,0,0] op_sel_hi:[1,1,1]
	v_pk_fma_f32 v[120:121], v[92:93], v[62:63], v[120:121] op_sel:[1,0,0] op_sel_hi:[1,1,1]
	ds_read_b128 v[0:3], v154 offset:15360
	ds_read_b128 v[4:7], v154 offset:15376
	v_add_f32_e32 v158, v158, v159
	v_add_f32_dpp v155, v155, v155 quad_perm:[1,0,3,2] row_mask:0xf bank_mask:0xf bound_ctrl:1
	s_mov_b32 s6, 0x1010101
	s_mov_b32 s7, 0x1010101
	v_add_f32_dpp v158, v158, v158 quad_perm:[1,0,3,2] row_mask:0xf bank_mask:0xf bound_ctrl:1
	v_add_f32_dpp v155, v155, v155 quad_perm:[2,3,0,1] row_mask:0xf bank_mask:0xf bound_ctrl:1
	s_nop 0
	v_add_f32_dpp v158, v158, v158 quad_perm:[2,3,0,1] row_mask:0xf bank_mask:0xf bound_ctrl:1
	v_add_f32_dpp v156, v155, v155 row_half_mirror row_mask:0xf bank_mask:0xf bound_ctrl:1
	v_pk_fma_f32 v[126:127], v[156:157], v[72:73], v[126:127] op_sel_hi:[0,1,1]
	v_pk_fma_f32 v[124:125], v[156:157], v[74:75], v[124:125] op_sel_hi:[0,1,1]
	v_add_f32_dpp v158, v158, v158 row_half_mirror row_mask:0xf bank_mask:0xf bound_ctrl:1
	v_pk_fma_f32 v[122:123], v[156:157], v[76:77], v[122:123] op_sel_hi:[0,1,1]
	v_pk_fma_f32 v[120:121], v[156:157], v[78:79], v[120:121] op_sel_hi:[0,1,1]
	v_cndmask_b32_e64 v94, v94, v158, s[6:7]
	ds_read_b128 v[64:67], v154 offset:17664
	ds_read_b128 v[68:71], v154 offset:17680
	ds_read_b128 v[56:59], v154 offset:17408
	ds_read_b128 v[60:63], v154 offset:17424
	ds_read_b128 v[72:75], v154 offset:17920
	ds_read_b128 v[76:79], v154 offset:17936
	s_waitcnt lgkmcnt(6)
	v_pk_mul_f32 v[156:157], v[24:25], v[126:127]
	v_pk_mul_f32 v[90:91], v[28:29], v[122:123]
	v_pk_mul_f32 v[158:159], v[40:41], v[126:127]
	v_pk_fma_f32 v[156:157], v[124:125], v[26:27], v[156:157]
	v_pk_fma_f32 v[90:91], v[120:121], v[30:31], v[90:91]
	v_pk_fma_f32 v[158:159], v[124:125], v[42:43], v[158:159]
	v_pk_fma_f32 v[126:127], v[98:99], v[16:17], v[126:127] op_sel_hi:[0,1,1]
	v_pk_fma_f32 v[158:159], v[122:123], v[44:45], v[158:159]
	v_pk_fma_f32 v[124:125], v[98:99], v[18:19], v[124:125] op_sel_hi:[0,1,1]
	v_pk_add_f32 v[156:157], v[156:157], v[90:91]
	v_pk_fma_f32 v[158:159], v[120:121], v[46:47], v[158:159]
	v_add_f32_e32 v155, v156, v157
	v_pk_fma_f32 v[122:123], v[98:99], v[20:21], v[122:123] op_sel_hi:[0,1,1]
	v_pk_fma_f32 v[120:121], v[98:99], v[22:23], v[120:121] op_sel_hi:[0,1,1]
	ds_read_b128 v[40:43], v154 offset:16896
	ds_read_b128 v[44:47], v154 offset:16912
	v_add_f32_e32 v158, v158, v159
	v_add_f32_dpp v155, v155, v155 quad_perm:[1,0,3,2] row_mask:0xf bank_mask:0xf bound_ctrl:1
	s_mov_b32 s6, 0x2020202
	s_mov_b32 s7, 0x2020202
	v_add_f32_dpp v158, v158, v158 quad_perm:[1,0,3,2] row_mask:0xf bank_mask:0xf bound_ctrl:1
	v_add_f32_dpp v155, v155, v155 quad_perm:[2,3,0,1] row_mask:0xf bank_mask:0xf bound_ctrl:1
	s_nop 0
	v_add_f32_dpp v158, v158, v158 quad_perm:[2,3,0,1] row_mask:0xf bank_mask:0xf bound_ctrl:1
	v_add_f32_dpp v156, v155, v155 row_half_mirror row_mask:0xf bank_mask:0xf bound_ctrl:1
	v_pk_fma_f32 v[126:127], v[156:157], v[32:33], v[126:127] op_sel_hi:[0,1,1]
	v_pk_fma_f32 v[124:125], v[156:157], v[34:35], v[124:125] op_sel_hi:[0,1,1]
	v_add_f32_dpp v158, v158, v158 row_half_mirror row_mask:0xf bank_mask:0xf bound_ctrl:1
	v_pk_fma_f32 v[122:123], v[156:157], v[36:37], v[122:123] op_sel_hi:[0,1,1]
	v_pk_fma_f32 v[120:121], v[156:157], v[38:39], v[120:121] op_sel_hi:[0,1,1]
	v_cndmask_b32_e64 v94, v94, v158, s[6:7]
	ds_read_b128 v[24:27], v154 offset:19200
	ds_read_b128 v[28:31], v154 offset:19216
	ds_read_b128 v[16:19], v154 offset:18944
	ds_read_b128 v[20:23], v154 offset:18960
	ds_read_b128 v[32:35], v154 offset:19456
	ds_read_b128 v[36:39], v154 offset:19472
	ds_read2st64_b32 v[92:93], v153 offset0:77 offset1:83
	s_waitcnt lgkmcnt(7)
; #define LAS __attribute__((address_space(3)))
; DI unsigned pack2(float lo, float hi) { f32x2 v = {lo, hi}; return __builtin_bit_cast(unsigned, __builtin_convertvector(v, bf16x2_t)); }
; DI void scan_item(PP p, int l, int item, LAS unsigned char* lds) {
;     ...
;     for (int c = 0; c < NCH; ++c) {
;         if (wid >= 4) { if (c + 1 < NCH) { fill(c + 1); if (c + 2 < NCH) gl(c + 2); } }
;         else {
;             const LAS float* sp = buf + ((c & 1) * T) * 384;
;             f32x4 Ar0, Ar1, Aw0, Aw1, Ak0, Ak1, Aa0, Aa1, Ab0, Ab1; float Avv;
;             f32x4 Br0, Br1, Bw0, Bw1, Bk0, Bk1, Ba0, Ba1, Bb0, Bb1; float Bvv;
;             SC_LD(A, sp);
;             const ptrdiff_t ystep = dir ? -512 : 512;
;             u16* Yl = Yp + (size_t)steprow(b, dir, c * T) * 512 + (ptrdiff_t)ks * ystep;
; #pragma nounroll
;             for (int st = 0; st < T; st += 2) {
;                 SC_LD(B, sp + (st + 1) * 384);
;                 SC_STEP(A, st);
;                 if (st + 2 < T) SC_LD(A, sp + (st + 2) * 384);
;                 SC_STEP(B, st + 1);
;                 if ((st & 6) == 6) {
;                     const LAS float* rp = ypl + (ks * 68 - lane) + (lane & ~7);
;                     const f32x4 q0 = *(const LAS f32x4*)rp, q1 = *(const LAS f32x4*)(rp + 4);
;                     Yl[(ptrdiff_t)(st - 6) * ystep] = (u16)(pack2(((q0[0] + q0[1]) + (q0[2] + q0[3])) + ((q1[0] + q1[1]) + (q1[2] + q1[3])), 0.f) & 0xffffu);
;                 }
	v_pk_mul_f32 v[156:157], v[64:65], v[126:127]
	v_pk_mul_f32 v[90:91], v[68:69], v[122:123]
	v_pk_mul_f32 v[158:159], v[0:1], v[126:127]
	v_pk_fma_f32 v[156:157], v[124:125], v[66:67], v[156:157]
	v_pk_fma_f32 v[90:91], v[120:121], v[70:71], v[90:91]
	v_pk_fma_f32 v[158:159], v[124:125], v[2:3], v[158:159]
	v_pk_fma_f32 v[126:127], v[98:99], v[56:57], v[126:127] op_sel:[1,0,0] op_sel_hi:[1,1,1]
	v_pk_fma_f32 v[158:159], v[122:123], v[4:5], v[158:159]
	v_pk_fma_f32 v[124:125], v[98:99], v[58:59], v[124:125] op_sel:[1,0,0] op_sel_hi:[1,1,1]
	v_pk_add_f32 v[156:157], v[156:157], v[90:91]
	v_pk_fma_f32 v[158:159], v[120:121], v[6:7], v[158:159]
	v_add_f32_e32 v155, v156, v157
	v_pk_fma_f32 v[122:123], v[98:99], v[60:61], v[122:123] op_sel:[1,0,0] op_sel_hi:[1,1,1]
	v_pk_fma_f32 v[120:121], v[98:99], v[62:63], v[120:121] op_sel:[1,0,0] op_sel_hi:[1,1,1]
	ds_read_b128 v[0:3], v154 offset:18432
	ds_read_b128 v[4:7], v154 offset:18448
	v_add_f32_e32 v158, v158, v159
	v_add_f32_dpp v155, v155, v155 quad_perm:[1,0,3,2] row_mask:0xf bank_mask:0xf bound_ctrl:1
	s_mov_b32 s6, 0x4040404
	s_mov_b32 s7, 0x4040404
	v_add_f32_dpp v158, v158, v158 quad_perm:[1,0,3,2] row_mask:0xf bank_mask:0xf bound_ctrl:1
	v_add_f32_dpp v155, v155, v155 quad_perm:[2,3,0,1] row_mask:0xf bank_mask:0xf bound_ctrl:1
	s_nop 0
	v_add_f32_dpp v158, v158, v158 quad_perm:[2,3,0,1] row_mask:0xf bank_mask:0xf bound_ctrl:1
	v_add_f32_dpp v156, v155, v155 row_half_mirror row_mask:0xf bank_mask:0xf bound_ctrl:1
	v_pk_fma_f32 v[126:127], v[156:157], v[72:73], v[126:127] op_sel_hi:[0,1,1]
	v_pk_fma_f32 v[124:125], v[156:157], v[74:75], v[124:125] op_sel_hi:[0,1,1]
	v_add_f32_dpp v158, v158, v158 row_half_mirror row_mask:0xf bank_mask:0xf bound_ctrl:1
	v_pk_fma_f32 v[122:123], v[156:157], v[76:77], v[122:123] op_sel_hi:[0,1,1]
	v_pk_fma_f32 v[120:121], v[156:157], v[78:79], v[120:121] op_sel_hi:[0,1,1]
	v_cndmask_b32_e64 v94, v94, v158, s[6:7]
	ds_read_b128 v[64:67], v154 offset:20736
	ds_read_b128 v[68:71], v154 offset:20752
	ds_read_b128 v[56:59], v154 offset:20480
	ds_read_b128 v[60:63], v154 offset:20496
	ds_read_b128 v[72:75], v154 offset:20992
	ds_read_b128 v[76:79], v154 offset:21008
	s_waitcnt lgkmcnt(6)
	v_pk_mul_f32 v[156:157], v[24:25], v[126:127]
	v_pk_mul_f32 v[90:91], v[28:29], v[122:123]
	v_pk_mul_f32 v[158:159], v[40:41], v[126:127]
	v_pk_fma_f32 v[156:157], v[124:125], v[26:27], v[156:157]
	v_pk_fma_f32 v[90:91], v[120:121], v[30:31], v[90:91]
	v_pk_fma_f32 v[158:159], v[124:125], v[42:43], v[158:159]
	v_pk_fma_f32 v[126:127], v[92:93], v[16:17], v[126:127] op_sel_hi:[0,1,1]
	v_pk_fma_f32 v[158:159], v[122:123], v[44:45], v[158:159]
	v_pk_fma_f32 v[124:125], v[92:93], v[18:19], v[124:125] op_sel_hi:[0,1,1]
	v_pk_add_f32 v[156:157], v[156:157], v[90:91]
	v_pk_fma_f32 v[158:159], v[120:121], v[46:47], v[158:159]
	v_add_f32_e32 v155, v156, v157
	v_pk_fma_f32 v[122:123], v[92:93], v[20:21], v[122:123] op_sel_hi:[0,1,1]
	v_pk_fma_f32 v[120:121], v[92:93], v[22:23], v[120:121] op_sel_hi:[0,1,1]
	ds_read_b128 v[40:43], v154 offset:19968
	ds_read_b128 v[44:47], v154 offset:19984
	v_add_f32_e32 v158, v158, v159
	v_add_f32_dpp v155, v155, v155 quad_perm:[1,0,3,2] row_mask:0xf bank_mask:0xf bound_ctrl:1
	s_mov_b32 s6, 0x8080808
	s_mov_b32 s7, 0x8080808
	v_add_f32_dpp v158, v158, v158 quad_perm:[1,0,3,2] row_mask:0xf bank_mask:0xf bound_ctrl:1
	v_add_f32_dpp v155, v155, v155 quad_perm:[2,3,0,1] row_mask:0xf bank_mask:0xf bound_ctrl:1
	s_nop 0
	v_add_f32_dpp v158, v158, v158 quad_perm:[2,3,0,1] row_mask:0xf bank_mask:0xf bound_ctrl:1
	v_add_f32_dpp v156, v155, v155 row_half_mirror row_mask:0xf bank_mask:0xf bound_ctrl:1
	v_pk_fma_f32 v[126:127], v[156:157], v[32:33], v[126:127] op_sel_hi:[0,1,1]
	v_pk_fma_f32 v[124:125], v[156:157], v[34:35], v[124:125] op_sel_hi:[0,1,1]
	v_add_f32_dpp v158, v158, v158 row_half_mirror row_mask:0xf bank_mask:0xf bound_ctrl:1
	v_pk_fma_f32 v[122:123], v[156:157], v[36:37], v[122:123] op_sel_hi:[0,1,1]
	v_pk_fma_f32 v[120:121], v[156:157], v[38:39], v[120:121] op_sel_hi:[0,1,1]
	v_cndmask_b32_e64 v94, v94, v158, s[6:7]
	ds_read_b128 v[24:27], v154 offset:22272
	ds_read_b128 v[28:31], v154 offset:22288
	ds_read_b128 v[16:19], v154 offset:22016
	ds_read_b128 v[20:23], v154 offset:22032
	ds_read_b128 v[32:35], v154 offset:22528
	ds_read_b128 v[36:39], v154 offset:22544
	ds_read2st64_b32 v[98:99], v153 offset0:89 offset1:95
	s_waitcnt lgkmcnt(7)
	v_pk_mul_f32 v[156:157], v[64:65], v[126:127]
	v_pk_mul_f32 v[90:91], v[68:69], v[122:123]
	v_pk_mul_f32 v[158:159], v[0:1], v[126:127]
	v_pk_fma_f32 v[156:157], v[124:125], v[66:67], v[156:157]
	v_pk_fma_f32 v[90:91], v[120:121], v[70:71], v[90:91]
	v_pk_fma_f32 v[158:159], v[124:125], v[2:3], v[158:159]
	v_pk_fma_f32 v[126:127], v[92:93], v[56:57], v[126:127] op_sel:[1,0,0] op_sel_hi:[1,1,1]
	v_pk_fma_f32 v[158:159], v[122:123], v[4:5], v[158:159]
	v_pk_fma_f32 v[124:125], v[92:93], v[58:59], v[124:125] op_sel:[1,0,0] op_sel_hi:[1,1,1]
	v_pk_add_f32 v[156:157], v[156:157], v[90:91]
	v_pk_fma_f32 v[158:159], v[120:121], v[6:7], v[158:159]
	v_add_f32_e32 v155, v156, v157
	v_pk_fma_f32 v[122:123], v[92:93], v[60:61], v[122:123] op_sel:[1,0,0] op_sel_hi:[1,1,1]
	v_pk_fma_f32 v[120:121], v[92:93], v[62:63], v[120:121] op_sel:[1,0,0] op_sel_hi:[1,1,1]
	ds_read_b128 v[0:3], v154 offset:21504
	ds_read_b128 v[4:7], v154 offset:21520
	v_add_f32_e32 v158, v158, v159
	v_add_f32_dpp v155, v155, v155 quad_perm:[1,0,3,2] row_mask:0xf bank_mask:0xf bound_ctrl:1
	s_mov_b32 s6, 0x10101010
	s_mov_b32 s7, 0x10101010
	v_add_f32_dpp v158, v158, v158 quad_perm:[1,0,3,2] row_mask:0xf bank_mask:0xf bound_ctrl:1
	v_add_f32_dpp v155, v155, v155 quad_perm:[2,3,0,1] row_mask:0xf bank_mask:0xf bound_ctrl:1
	s_nop 0
	v_add_f32_dpp v158, v158, v158 quad_perm:[2,3,0,1] row_mask:0xf bank_mask:0xf bound_ctrl:1
	v_add_f32_dpp v156, v155, v155 row_half_mirror row_mask:0xf bank_mask:0xf bound_ctrl:1
	v_pk_fma_f32 v[126:127], v[156:157], v[72:73], v[126:127] op_sel_hi:[0,1,1]
	v_pk_fma_f32 v[124:125], v[156:157], v[74:75], v[124:125] op_sel_hi:[0,1,1]
	v_add_f32_dpp v158, v158, v158 row_half_mirror row_mask:0xf bank_mask:0xf bound_ctrl:1
	v_pk_fma_f32 v[122:123], v[156:157], v[76:77], v[122:123] op_sel_hi:[0,1,1]
	v_pk_fma_f32 v[120:121], v[156:157], v[78:79], v[120:121] op_sel_hi:[0,1,1]
	v_cndmask_b32_e64 v94, v94, v158, s[6:7]
	ds_read_b128 v[64:67], v154 offset:23808
	ds_read_b128 v[68:71], v154 offset:23824
	ds_read_b128 v[56:59], v154 offset:23552
	ds_read_b128 v[60:63], v154 offset:23568
	ds_read_b128 v[72:75], v154 offset:24064
	ds_read_b128 v[76:79], v154 offset:24080
	ds_read_b128 v[48:51], v154 offset:23296
	ds_read_b128 v[52:55], v154 offset:23312
	s_waitcnt lgkmcnt(8)
; #define LAS __attribute__((address_space(3)))
; DI unsigned pack2(float lo, float hi) { f32x2 v = {lo, hi}; return __builtin_bit_cast(unsigned, __builtin_convertvector(v, bf16x2_t)); }
; DI void scan_item(PP p, int l, int item, LAS unsigned char* lds) {
;     ...
;     for (int c = 0; c < NCH; ++c) {
;         if (wid >= 4) { if (c + 1 < NCH) { fill(c + 1); if (c + 2 < NCH) gl(c + 2); } }
;         else {
;             const LAS float* sp = buf + ((c & 1) * T) * 384;
;             f32x4 Ar0, Ar1, Aw0, Aw1, Ak0, Ak1, Aa0, Aa1, Ab0, Ab1; float Avv;
;             f32x4 Br0, Br1, Bw0, Bw1, Bk0, Bk1, Ba0, Ba1, Bb0, Bb1; float Bvv;
;             SC_LD(A, sp);
;             const ptrdiff_t ystep = dir ? -512 : 512;
;             u16* Yl = Yp + (size_t)steprow(b, dir, c * T) * 512 + (ptrdiff_t)ks * ystep;
; #pragma nounroll
;             for (int st = 0; st < T; st += 2) {
;                 SC_LD(B, sp + (st + 1) * 384);
;                 SC_STEP(A, st);
;                 if (st + 2 < T) SC_LD(A, sp + (st + 2) * 384);
;                 SC_STEP(B, st + 1);
;                 if ((st & 6) == 6) {
;                     const LAS float* rp = ypl + (ks * 68 - lane) + (lane & ~7);
;                     const f32x4 q0 = *(const LAS f32x4*)rp, q1 = *(const LAS f32x4*)(rp + 4);
;                     Yl[(ptrdiff_t)(st - 6) * ystep] = (u16)(pack2(((q0[0] + q0[1]) + (q0[2] + q0[3])) + ((q1[0] + q1[1]) + (q1[2] + q1[3])), 0.f) & 0xffffu);
;                 }
	v_pk_mul_f32 v[156:157], v[24:25], v[126:127]
	v_pk_mul_f32 v[90:91], v[28:29], v[122:123]
	v_pk_mul_f32 v[158:159], v[40:41], v[126:127]
	v_pk_fma_f32 v[156:157], v[124:125], v[26:27], v[156:157]
	v_pk_fma_f32 v[90:91], v[120:121], v[30:31], v[90:91]
	v_pk_fma_f32 v[158:159], v[124:125], v[42:43], v[158:159]
	v_pk_fma_f32 v[126:127], v[98:99], v[16:17], v[126:127] op_sel_hi:[0,1,1]
	v_pk_fma_f32 v[158:159], v[122:123], v[44:45], v[158:159]
	v_pk_fma_f32 v[124:125], v[98:99], v[18:19], v[124:125] op_sel_hi:[0,1,1]
	v_pk_add_f32 v[156:157], v[156:157], v[90:91]
	v_pk_fma_f32 v[158:159], v[120:121], v[46:47], v[158:159]
	v_add_f32_e32 v155, v156, v157
	v_pk_fma_f32 v[122:123], v[98:99], v[20:21], v[122:123] op_sel_hi:[0,1,1]
	v_pk_fma_f32 v[120:121], v[98:99], v[22:23], v[120:121] op_sel_hi:[0,1,1]
	ds_read_b128 v[40:43], v154 offset:23040
	ds_read_b128 v[44:47], v154 offset:23056
	v_add_f32_e32 v158, v158, v159
	v_add_f32_dpp v155, v155, v155 quad_perm:[1,0,3,2] row_mask:0xf bank_mask:0xf bound_ctrl:1
	s_mov_b32 s6, 0x20202020
	s_mov_b32 s7, 0x20202020
	v_add_f32_dpp v158, v158, v158 quad_perm:[1,0,3,2] row_mask:0xf bank_mask:0xf bound_ctrl:1
	v_add_f32_dpp v155, v155, v155 quad_perm:[2,3,0,1] row_mask:0xf bank_mask:0xf bound_ctrl:1
	s_nop 0
	v_add_f32_dpp v158, v158, v158 quad_perm:[2,3,0,1] row_mask:0xf bank_mask:0xf bound_ctrl:1
	v_add_f32_dpp v156, v155, v155 row_half_mirror row_mask:0xf bank_mask:0xf bound_ctrl:1
	v_pk_fma_f32 v[126:127], v[156:157], v[32:33], v[126:127] op_sel_hi:[0,1,1]
	v_pk_fma_f32 v[124:125], v[156:157], v[34:35], v[124:125] op_sel_hi:[0,1,1]
	v_add_f32_dpp v158, v158, v158 row_half_mirror row_mask:0xf bank_mask:0xf bound_ctrl:1
	v_pk_fma_f32 v[122:123], v[156:157], v[36:37], v[122:123] op_sel_hi:[0,1,1]
	v_pk_fma_f32 v[120:121], v[156:157], v[38:39], v[120:121] op_sel_hi:[0,1,1]
	v_cndmask_b32_e64 v94, v94, v158, s[6:7]
	ds_read_b128 v[24:27], v154 offset:25344
	ds_read_b128 v[28:31], v154 offset:25360
	ds_read_b128 v[16:19], v154 offset:25088
	ds_read_b128 v[20:23], v154 offset:25104
	ds_read_b128 v[32:35], v154 offset:25600
	ds_read_b128 v[36:39], v154 offset:25616
	ds_read2st64_b32 v[92:93], v153 offset0:101 offset1:107
	s_waitcnt lgkmcnt(7)
	v_pk_mul_f32 v[156:157], v[64:65], v[126:127]
	v_pk_mul_f32 v[90:91], v[68:69], v[122:123]
	v_pk_mul_f32 v[158:159], v[0:1], v[126:127]
	v_pk_fma_f32 v[156:157], v[124:125], v[66:67], v[156:157]
	v_pk_fma_f32 v[90:91], v[120:121], v[70:71], v[90:91]
	v_pk_fma_f32 v[158:159], v[124:125], v[2:3], v[158:159]
	v_pk_fma_f32 v[126:127], v[98:99], v[56:57], v[126:127] op_sel:[1,0,0] op_sel_hi:[1,1,1]
	v_pk_fma_f32 v[158:159], v[122:123], v[4:5], v[158:159]
	v_pk_fma_f32 v[124:125], v[98:99], v[58:59], v[124:125] op_sel:[1,0,0] op_sel_hi:[1,1,1]
	v_pk_add_f32 v[156:157], v[156:157], v[90:91]
	v_pk_fma_f32 v[158:159], v[120:121], v[6:7], v[158:159]
	v_add_f32_e32 v155, v156, v157
	v_pk_fma_f32 v[122:123], v[98:99], v[60:61], v[122:123] op_sel:[1,0,0] op_sel_hi:[1,1,1]
	v_pk_fma_f32 v[120:121], v[98:99], v[62:63], v[120:121] op_sel:[1,0,0] op_sel_hi:[1,1,1]
	ds_read_b128 v[0:3], v154 offset:24576
	ds_read_b128 v[4:7], v154 offset:24592
	v_add_f32_e32 v158, v158, v159
	v_add_f32_dpp v155, v155, v155 quad_perm:[1,0,3,2] row_mask:0xf bank_mask:0xf bound_ctrl:1
	s_mov_b32 s6, 0x40404040
	s_mov_b32 s7, 0x40404040
	v_add_f32_dpp v158, v158, v158 quad_perm:[1,0,3,2] row_mask:0xf bank_mask:0xf bound_ctrl:1
	v_add_f32_dpp v155, v155, v155 quad_perm:[2,3,0,1] row_mask:0xf bank_mask:0xf bound_ctrl:1
	s_nop 0
	v_add_f32_dpp v158, v158, v158 quad_perm:[2,3,0,1] row_mask:0xf bank_mask:0xf bound_ctrl:1
	v_add_f32_dpp v156, v155, v155 row_half_mirror row_mask:0xf bank_mask:0xf bound_ctrl:1
	v_pk_fma_f32 v[126:127], v[156:157], v[72:73], v[126:127] op_sel_hi:[0,1,1]
	v_pk_fma_f32 v[124:125], v[156:157], v[74:75], v[124:125] op_sel_hi:[0,1,1]
	v_add_f32_dpp v158, v158, v158 row_half_mirror row_mask:0xf bank_mask:0xf bound_ctrl:1
	v_pk_fma_f32 v[122:123], v[156:157], v[76:77], v[122:123] op_sel_hi:[0,1,1]
	v_pk_fma_f32 v[120:121], v[156:157], v[78:79], v[120:121] op_sel_hi:[0,1,1]
	v_cndmask_b32_e64 v94, v94, v158, s[6:7]
	v_pk_mul_f32 v[158:159], v[40:41], v[126:127]
	v_pk_mul_f32 v[126:127], v[48:49], v[126:127]
	v_pk_fma_f32 v[158:159], v[124:125], v[42:43], v[158:159]
	v_pk_mul_f32 v[124:125], v[50:51], v[124:125]
	v_pk_fma_f32 v[158:159], v[122:123], v[44:45], v[158:159]
	v_pk_mul_f32 v[122:123], v[52:53], v[122:123]
	v_pk_fma_f32 v[158:159], v[120:121], v[46:47], v[158:159]
	v_pk_mul_f32 v[120:121], v[54:55], v[120:121]
	v_add_f32_e32 v158, v158, v159
	s_mov_b32 s6, 0x80808080
	s_mov_b32 s7, 0x80808080
	v_add_f32_dpp v158, v158, v158 quad_perm:[1,0,3,2] row_mask:0xf bank_mask:0xf bound_ctrl:1
	s_nop 1
	v_add_f32_dpp v158, v158, v158 quad_perm:[2,3,0,1] row_mask:0xf bank_mask:0xf bound_ctrl:1
	s_nop 1
	v_add_f32_dpp v158, v158, v158 row_half_mirror row_mask:0xf bank_mask:0xf bound_ctrl:1
	v_cndmask_b32_e64 v94, v94, v158, s[6:7]
	ds_read_b128 v[40:43], v154 offset:26112
	ds_read_b128 v[44:47], v154 offset:26128
	ds_read_b128 v[64:67], v154 offset:26880
	ds_read_b128 v[68:71], v154 offset:26896
	ds_read_b128 v[56:59], v154 offset:26624
	ds_read_b128 v[60:63], v154 offset:26640
	ds_read_b128 v[72:75], v154 offset:27136
	ds_read_b128 v[76:79], v154 offset:27152
	s_waitcnt lgkmcnt(8)
; #define LAS __attribute__((address_space(3)))
; DI unsigned pack2(float lo, float hi) { f32x2 v = {lo, hi}; return __builtin_bit_cast(unsigned, __builtin_convertvector(v, bf16x2_t)); }
; DI void scan_item(PP p, int l, int item, LAS unsigned char* lds) {
;     ...
;     for (int c = 0; c < NCH; ++c) {
;         if (wid >= 4) { if (c + 1 < NCH) { fill(c + 1); if (c + 2 < NCH) gl(c + 2); } }
;         else {
;             const LAS float* sp = buf + ((c & 1) * T) * 384;
;             f32x4 Ar0, Ar1, Aw0, Aw1, Ak0, Ak1, Aa0, Aa1, Ab0, Ab1; float Avv;
;             f32x4 Br0, Br1, Bw0, Bw1, Bk0, Bk1, Ba0, Ba1, Bb0, Bb1; float Bvv;
;             SC_LD(A, sp);
;             const ptrdiff_t ystep = dir ? -512 : 512;
;             u16* Yl = Yp + (size_t)steprow(b, dir, c * T) * 512 + (ptrdiff_t)ks * ystep;
; #pragma nounroll
;             for (int st = 0; st < T; st += 2) {
;                 SC_LD(B, sp + (st + 1) * 384);
;                 SC_STEP(A, st);
;                 if (st + 2 < T) SC_LD(A, sp + (st + 2) * 384);
;                 SC_STEP(B, st + 1);
;                 if ((st & 6) == 6) {
;                     const LAS float* rp = ypl + (ks * 68 - lane) + (lane & ~7);
;                     const f32x4 q0 = *(const LAS f32x4*)rp, q1 = *(const LAS f32x4*)(rp + 4);
;                     Yl[(ptrdiff_t)(st - 6) * ystep] = (u16)(pack2(((q0[0] + q0[1]) + (q0[2] + q0[3])) + ((q1[0] + q1[1]) + (q1[2] + q1[3])), 0.f) & 0xffffu);
;                 }
	v_pk_mul_f32 v[156:157], v[24:25], v[126:127]
	v_pk_mul_f32 v[90:91], v[28:29], v[122:123]
	v_pk_fma_f32 v[126:127], v[92:93], v[16:17], v[126:127] op_sel_hi:[0,1,1]
	v_pk_fma_f32 v[156:157], v[124:125], v[26:27], v[156:157]
	v_pk_fma_f32 v[90:91], v[120:121], v[30:31], v[90:91]
	v_pk_fma_f32 v[124:125], v[92:93], v[18:19], v[124:125] op_sel_hi:[0,1,1]
	v_pk_fma_f32 v[122:123], v[92:93], v[20:21], v[122:123] op_sel_hi:[0,1,1]
	v_pk_add_f32 v[156:157], v[156:157], v[90:91]
	v_pk_fma_f32 v[120:121], v[92:93], v[22:23], v[120:121] op_sel_hi:[0,1,1]
	v_add_f32_e32 v155, v156, v157
	s_nop 1
	v_add_f32_dpp v155, v155, v155 quad_perm:[1,0,3,2] row_mask:0xf bank_mask:0xf bound_ctrl:1
	s_nop 1
	v_add_f32_dpp v155, v155, v155 quad_perm:[2,3,0,1] row_mask:0xf bank_mask:0xf bound_ctrl:1
	s_nop 1
	v_add_f32_dpp v156, v155, v155 row_half_mirror row_mask:0xf bank_mask:0xf bound_ctrl:1
	v_pk_fma_f32 v[126:127], v[156:157], v[32:33], v[126:127] op_sel_hi:[0,1,1]
	v_pk_fma_f32 v[124:125], v[156:157], v[34:35], v[124:125] op_sel_hi:[0,1,1]
	v_pk_fma_f32 v[122:123], v[156:157], v[36:37], v[122:123] op_sel_hi:[0,1,1]
	v_pk_fma_f32 v[120:121], v[156:157], v[38:39], v[120:121] op_sel_hi:[0,1,1]
	v_cvt_pk_bf16_f32 v82, v94, v94
	global_store_short v[118:119], v82, off
	v_lshl_add_u64 v[118:119], s[8:9], 0, v[118:119]
	ds_read_b128 v[24:27], v154 offset:28416
	ds_read_b128 v[28:31], v154 offset:28432
	ds_read_b128 v[16:19], v154 offset:28160
	ds_read_b128 v[20:23], v154 offset:28176
	ds_read_b128 v[32:35], v154 offset:28672
	ds_read_b128 v[36:39], v154 offset:28688
	ds_read2st64_b32 v[98:99], v153 offset0:113 offset1:119
	s_waitcnt lgkmcnt(7)
	v_pk_mul_f32 v[156:157], v[64:65], v[126:127]
	v_pk_mul_f32 v[90:91], v[68:69], v[122:123]
	v_pk_mul_f32 v[158:159], v[0:1], v[126:127]
	v_pk_fma_f32 v[156:157], v[124:125], v[66:67], v[156:157]
	v_pk_fma_f32 v[90:91], v[120:121], v[70:71], v[90:91]
	v_pk_fma_f32 v[158:159], v[124:125], v[2:3], v[158:159]
	v_pk_fma_f32 v[126:127], v[92:93], v[56:57], v[126:127] op_sel:[1,0,0] op_sel_hi:[1,1,1]
	v_pk_fma_f32 v[158:159], v[122:123], v[4:5], v[158:159]
	v_pk_fma_f32 v[124:125], v[92:93], v[58:59], v[124:125] op_sel:[1,0,0] op_sel_hi:[1,1,1]
	v_pk_add_f32 v[156:157], v[156:157], v[90:91]
	v_pk_fma_f32 v[158:159], v[120:121], v[6:7], v[158:159]
	v_add_f32_e32 v155, v156, v157
	v_pk_fma_f32 v[122:123], v[92:93], v[60:61], v[122:123] op_sel:[1,0,0] op_sel_hi:[1,1,1]
	v_pk_fma_f32 v[120:121], v[92:93], v[62:63], v[120:121] op_sel:[1,0,0] op_sel_hi:[1,1,1]
	ds_read_b128 v[0:3], v154 offset:27648
	ds_read_b128 v[4:7], v154 offset:27664
	v_add_f32_e32 v158, v158, v159
	v_add_f32_dpp v155, v155, v155 quad_perm:[1,0,3,2] row_mask:0xf bank_mask:0xf bound_ctrl:1
	s_mov_b32 s6, 0x1010101
	s_mov_b32 s7, 0x1010101
	v_add_f32_dpp v158, v158, v158 quad_perm:[1,0,3,2] row_mask:0xf bank_mask:0xf bound_ctrl:1
	v_add_f32_dpp v155, v155, v155 quad_perm:[2,3,0,1] row_mask:0xf bank_mask:0xf bound_ctrl:1
	s_nop 0
	v_add_f32_dpp v158, v158, v158 quad_perm:[2,3,0,1] row_mask:0xf bank_mask:0xf bound_ctrl:1
	v_add_f32_dpp v156, v155, v155 row_half_mirror row_mask:0xf bank_mask:0xf bound_ctrl:1
	v_pk_fma_f32 v[126:127], v[156:157], v[72:73], v[126:127] op_sel_hi:[0,1,1]
	v_pk_fma_f32 v[124:125], v[156:157], v[74:75], v[124:125] op_sel_hi:[0,1,1]
	v_add_f32_dpp v158, v158, v158 row_half_mirror row_mask:0xf bank_mask:0xf bound_ctrl:1
	v_pk_fma_f32 v[122:123], v[156:157], v[76:77], v[122:123] op_sel_hi:[0,1,1]
	v_pk_fma_f32 v[120:121], v[156:157], v[78:79], v[120:121] op_sel_hi:[0,1,1]
	v_cndmask_b32_e64 v94, v94, v158, s[6:7]
	ds_read_b128 v[64:67], v154 offset:29952
	ds_read_b128 v[68:71], v154 offset:29968
	ds_read_b128 v[56:59], v154 offset:29696
	ds_read_b128 v[60:63], v154 offset:29712
	ds_read_b128 v[72:75], v154 offset:30208
	ds_read_b128 v[76:79], v154 offset:30224
	s_waitcnt lgkmcnt(6)
	v_pk_mul_f32 v[156:157], v[24:25], v[126:127]
	v_pk_mul_f32 v[90:91], v[28:29], v[122:123]
	v_pk_mul_f32 v[158:159], v[40:41], v[126:127]
	v_pk_fma_f32 v[156:157], v[124:125], v[26:27], v[156:157]
	v_pk_fma_f32 v[90:91], v[120:121], v[30:31], v[90:91]
	v_pk_fma_f32 v[158:159], v[124:125], v[42:43], v[158:159]
	v_pk_fma_f32 v[126:127], v[98:99], v[16:17], v[126:127] op_sel_hi:[0,1,1]
	v_pk_fma_f32 v[158:159], v[122:123], v[44:45], v[158:159]
	v_pk_fma_f32 v[124:125], v[98:99], v[18:19], v[124:125] op_sel_hi:[0,1,1]
	v_pk_add_f32 v[156:157], v[156:157], v[90:91]
	v_pk_fma_f32 v[158:159], v[120:121], v[46:47], v[158:159]
	v_add_f32_e32 v155, v156, v157
	v_pk_fma_f32 v[122:123], v[98:99], v[20:21], v[122:123] op_sel_hi:[0,1,1]
	v_pk_fma_f32 v[120:121], v[98:99], v[22:23], v[120:121] op_sel_hi:[0,1,1]
	ds_read_b128 v[40:43], v154 offset:29184
	ds_read_b128 v[44:47], v154 offset:29200
	v_add_f32_e32 v158, v158, v159
	v_add_f32_dpp v155, v155, v155 quad_perm:[1,0,3,2] row_mask:0xf bank_mask:0xf bound_ctrl:1
	s_mov_b32 s6, 0x2020202
	s_mov_b32 s7, 0x2020202
	v_add_f32_dpp v158, v158, v158 quad_perm:[1,0,3,2] row_mask:0xf bank_mask:0xf bound_ctrl:1
	v_add_f32_dpp v155, v155, v155 quad_perm:[2,3,0,1] row_mask:0xf bank_mask:0xf bound_ctrl:1
	s_nop 0
	v_add_f32_dpp v158, v158, v158 quad_perm:[2,3,0,1] row_mask:0xf bank_mask:0xf bound_ctrl:1
	v_add_f32_dpp v156, v155, v155 row_half_mirror row_mask:0xf bank_mask:0xf bound_ctrl:1
	v_pk_fma_f32 v[126:127], v[156:157], v[32:33], v[126:127] op_sel_hi:[0,1,1]
	v_pk_fma_f32 v[124:125], v[156:157], v[34:35], v[124:125] op_sel_hi:[0,1,1]
	v_add_f32_dpp v158, v158, v158 row_half_mirror row_mask:0xf bank_mask:0xf bound_ctrl:1
	v_pk_fma_f32 v[122:123], v[156:157], v[36:37], v[122:123] op_sel_hi:[0,1,1]
	v_pk_fma_f32 v[120:121], v[156:157], v[38:39], v[120:121] op_sel_hi:[0,1,1]
	v_cndmask_b32_e64 v94, v94, v158, s[6:7]
	ds_read_b128 v[24:27], v154 offset:31488
	ds_read_b128 v[28:31], v154 offset:31504
	ds_read_b128 v[16:19], v154 offset:31232
	ds_read_b128 v[20:23], v154 offset:31248
	ds_read_b128 v[32:35], v154 offset:31744
	ds_read_b128 v[36:39], v154 offset:31760
	ds_read2st64_b32 v[92:93], v153 offset0:125 offset1:131
	s_waitcnt lgkmcnt(7)
; #define LAS __attribute__((address_space(3)))
; DI unsigned pack2(float lo, float hi) { f32x2 v = {lo, hi}; return __builtin_bit_cast(unsigned, __builtin_convertvector(v, bf16x2_t)); }
; DI void scan_item(PP p, int l, int item, LAS unsigned char* lds) {
;     ...
;     for (int c = 0; c < NCH; ++c) {
;         if (wid >= 4) { if (c + 1 < NCH) { fill(c + 1); if (c + 2 < NCH) gl(c + 2); } }
;         else {
;             const LAS float* sp = buf + ((c & 1) * T) * 384;
;             f32x4 Ar0, Ar1, Aw0, Aw1, Ak0, Ak1, Aa0, Aa1, Ab0, Ab1; float Avv;
;             f32x4 Br0, Br1, Bw0, Bw1, Bk0, Bk1, Ba0, Ba1, Bb0, Bb1; float Bvv;
;             SC_LD(A, sp);
;             const ptrdiff_t ystep = dir ? -512 : 512;
;             u16* Yl = Yp + (size_t)steprow(b, dir, c * T) * 512 + (ptrdiff_t)ks * ystep;
; #pragma nounroll
;             for (int st = 0; st < T; st += 2) {
;                 SC_LD(B, sp + (st + 1) * 384);
;                 SC_STEP(A, st);
;                 if (st + 2 < T) SC_LD(A, sp + (st + 2) * 384);
;                 SC_STEP(B, st + 1);
;                 if ((st & 6) == 6) {
;                     const LAS float* rp = ypl + (ks * 68 - lane) + (lane & ~7);
;                     const f32x4 q0 = *(const LAS f32x4*)rp, q1 = *(const LAS f32x4*)(rp + 4);
;                     Yl[(ptrdiff_t)(st - 6) * ystep] = (u16)(pack2(((q0[0] + q0[1]) + (q0[2] + q0[3])) + ((q1[0] + q1[1]) + (q1[2] + q1[3])), 0.f) & 0xffffu);
;                 }
	v_pk_mul_f32 v[156:157], v[64:65], v[126:127]
	v_pk_mul_f32 v[90:91], v[68:69], v[122:123]
	v_pk_mul_f32 v[158:159], v[0:1], v[126:127]
	v_pk_fma_f32 v[156:157], v[124:125], v[66:67], v[156:157]
	v_pk_fma_f32 v[90:91], v[120:121], v[70:71], v[90:91]
	v_pk_fma_f32 v[158:159], v[124:125], v[2:3], v[158:159]
	v_pk_fma_f32 v[126:127], v[98:99], v[56:57], v[126:127] op_sel:[1,0,0] op_sel_hi:[1,1,1]
	v_pk_fma_f32 v[158:159], v[122:123], v[4:5], v[158:159]
	v_pk_fma_f32 v[124:125], v[98:99], v[58:59], v[124:125] op_sel:[1,0,0] op_sel_hi:[1,1,1]
	v_pk_add_f32 v[156:157], v[156:157], v[90:91]
	v_pk_fma_f32 v[158:159], v[120:121], v[6:7], v[158:159]
	v_add_f32_e32 v155, v156, v157
	v_pk_fma_f32 v[122:123], v[98:99], v[60:61], v[122:123] op_sel:[1,0,0] op_sel_hi:[1,1,1]
	v_pk_fma_f32 v[120:121], v[98:99], v[62:63], v[120:121] op_sel:[1,0,0] op_sel_hi:[1,1,1]
	ds_read_b128 v[0:3], v154 offset:30720
	ds_read_b128 v[4:7], v154 offset:30736
	v_add_f32_e32 v158, v158, v159
	v_add_f32_dpp v155, v155, v155 quad_perm:[1,0,3,2] row_mask:0xf bank_mask:0xf bound_ctrl:1
	s_mov_b32 s6, 0x4040404
	s_mov_b32 s7, 0x4040404
	v_add_f32_dpp v158, v158, v158 quad_perm:[1,0,3,2] row_mask:0xf bank_mask:0xf bound_ctrl:1
	v_add_f32_dpp v155, v155, v155 quad_perm:[2,3,0,1] row_mask:0xf bank_mask:0xf bound_ctrl:1
	s_nop 0
	v_add_f32_dpp v158, v158, v158 quad_perm:[2,3,0,1] row_mask:0xf bank_mask:0xf bound_ctrl:1
	v_add_f32_dpp v156, v155, v155 row_half_mirror row_mask:0xf bank_mask:0xf bound_ctrl:1
	v_pk_fma_f32 v[126:127], v[156:157], v[72:73], v[126:127] op_sel_hi:[0,1,1]
	v_pk_fma_f32 v[124:125], v[156:157], v[74:75], v[124:125] op_sel_hi:[0,1,1]
	v_add_f32_dpp v158, v158, v158 row_half_mirror row_mask:0xf bank_mask:0xf bound_ctrl:1
	v_pk_fma_f32 v[122:123], v[156:157], v[76:77], v[122:123] op_sel_hi:[0,1,1]
	v_pk_fma_f32 v[120:121], v[156:157], v[78:79], v[120:121] op_sel_hi:[0,1,1]
	v_cndmask_b32_e64 v94, v94, v158, s[6:7]
	ds_read_b128 v[64:67], v154 offset:33024
	ds_read_b128 v[68:71], v154 offset:33040
	ds_read_b128 v[56:59], v154 offset:32768
	ds_read_b128 v[60:63], v154 offset:32784
	ds_read_b128 v[72:75], v154 offset:33280
	ds_read_b128 v[76:79], v154 offset:33296
	s_waitcnt lgkmcnt(6)
	v_pk_mul_f32 v[156:157], v[24:25], v[126:127]
	v_pk_mul_f32 v[90:91], v[28:29], v[122:123]
	v_pk_mul_f32 v[158:159], v[40:41], v[126:127]
	v_pk_fma_f32 v[156:157], v[124:125], v[26:27], v[156:157]
	v_pk_fma_f32 v[90:91], v[120:121], v[30:31], v[90:91]
	v_pk_fma_f32 v[158:159], v[124:125], v[42:43], v[158:159]
	v_pk_fma_f32 v[126:127], v[92:93], v[16:17], v[126:127] op_sel_hi:[0,1,1]
	v_pk_fma_f32 v[158:159], v[122:123], v[44:45], v[158:159]
	v_pk_fma_f32 v[124:125], v[92:93], v[18:19], v[124:125] op_sel_hi:[0,1,1]
	v_pk_add_f32 v[156:157], v[156:157], v[90:91]
	v_pk_fma_f32 v[158:159], v[120:121], v[46:47], v[158:159]
	v_add_f32_e32 v155, v156, v157
	v_pk_fma_f32 v[122:123], v[92:93], v[20:21], v[122:123] op_sel_hi:[0,1,1]
	v_pk_fma_f32 v[120:121], v[92:93], v[22:23], v[120:121] op_sel_hi:[0,1,1]
	ds_read_b128 v[40:43], v154 offset:32256
	ds_read_b128 v[44:47], v154 offset:32272
	v_add_f32_e32 v158, v158, v159
	v_add_f32_dpp v155, v155, v155 quad_perm:[1,0,3,2] row_mask:0xf bank_mask:0xf bound_ctrl:1
	s_mov_b32 s6, 0x8080808
	s_mov_b32 s7, 0x8080808
	v_add_f32_dpp v158, v158, v158 quad_perm:[1,0,3,2] row_mask:0xf bank_mask:0xf bound_ctrl:1
	v_add_f32_dpp v155, v155, v155 quad_perm:[2,3,0,1] row_mask:0xf bank_mask:0xf bound_ctrl:1
	s_nop 0
	v_add_f32_dpp v158, v158, v158 quad_perm:[2,3,0,1] row_mask:0xf bank_mask:0xf bound_ctrl:1
	v_add_f32_dpp v156, v155, v155 row_half_mirror row_mask:0xf bank_mask:0xf bound_ctrl:1
	v_pk_fma_f32 v[126:127], v[156:157], v[32:33], v[126:127] op_sel_hi:[0,1,1]
	v_pk_fma_f32 v[124:125], v[156:157], v[34:35], v[124:125] op_sel_hi:[0,1,1]
	v_add_f32_dpp v158, v158, v158 row_half_mirror row_mask:0xf bank_mask:0xf bound_ctrl:1
	v_pk_fma_f32 v[122:123], v[156:157], v[36:37], v[122:123] op_sel_hi:[0,1,1]
	v_pk_fma_f32 v[120:121], v[156:157], v[38:39], v[120:121] op_sel_hi:[0,1,1]
	v_cndmask_b32_e64 v94, v94, v158, s[6:7]
	ds_read_b128 v[24:27], v154 offset:34560
	ds_read_b128 v[28:31], v154 offset:34576
	ds_read_b128 v[16:19], v154 offset:34304
	ds_read_b128 v[20:23], v154 offset:34320
	ds_read_b128 v[32:35], v154 offset:34816
	ds_read_b128 v[36:39], v154 offset:34832
	ds_read2st64_b32 v[98:99], v153 offset0:137 offset1:143
	s_waitcnt lgkmcnt(7)
	v_pk_mul_f32 v[156:157], v[64:65], v[126:127]
	v_pk_mul_f32 v[90:91], v[68:69], v[122:123]
	v_pk_mul_f32 v[158:159], v[0:1], v[126:127]
	v_pk_fma_f32 v[156:157], v[124:125], v[66:67], v[156:157]
	v_pk_fma_f32 v[90:91], v[120:121], v[70:71], v[90:91]
	v_pk_fma_f32 v[158:159], v[124:125], v[2:3], v[158:159]
	v_pk_fma_f32 v[126:127], v[92:93], v[56:57], v[126:127] op_sel:[1,0,0] op_sel_hi:[1,1,1]
	v_pk_fma_f32 v[158:159], v[122:123], v[4:5], v[158:159]
	v_pk_fma_f32 v[124:125], v[92:93], v[58:59], v[124:125] op_sel:[1,0,0] op_sel_hi:[1,1,1]
	v_pk_add_f32 v[156:157], v[156:157], v[90:91]
	v_pk_fma_f32 v[158:159], v[120:121], v[6:7], v[158:159]
	v_add_f32_e32 v155, v156, v157
	v_pk_fma_f32 v[122:123], v[92:93], v[60:61], v[122:123] op_sel:[1,0,0] op_sel_hi:[1,1,1]
	v_pk_fma_f32 v[120:121], v[92:93], v[62:63], v[120:121] op_sel:[1,0,0] op_sel_hi:[1,1,1]
	ds_read_b128 v[0:3], v154 offset:33792
	ds_read_b128 v[4:7], v154 offset:33808
	v_add_f32_e32 v158, v158, v159
	v_add_f32_dpp v155, v155, v155 quad_perm:[1,0,3,2] row_mask:0xf bank_mask:0xf bound_ctrl:1
	s_mov_b32 s6, 0x10101010
	s_mov_b32 s7, 0x10101010
	v_add_f32_dpp v158, v158, v158 quad_perm:[1,0,3,2] row_mask:0xf bank_mask:0xf bound_ctrl:1
	v_add_f32_dpp v155, v155, v155 quad_perm:[2,3,0,1] row_mask:0xf bank_mask:0xf bound_ctrl:1
	s_nop 0
	v_add_f32_dpp v158, v158, v158 quad_perm:[2,3,0,1] row_mask:0xf bank_mask:0xf bound_ctrl:1
	v_add_f32_dpp v156, v155, v155 row_half_mirror row_mask:0xf bank_mask:0xf bound_ctrl:1
	v_pk_fma_f32 v[126:127], v[156:157], v[72:73], v[126:127] op_sel_hi:[0,1,1]
	v_pk_fma_f32 v[124:125], v[156:157], v[74:75], v[124:125] op_sel_hi:[0,1,1]
	v_add_f32_dpp v158, v158, v158 row_half_mirror row_mask:0xf bank_mask:0xf bound_ctrl:1
	v_pk_fma_f32 v[122:123], v[156:157], v[76:77], v[122:123] op_sel_hi:[0,1,1]
	v_pk_fma_f32 v[120:121], v[156:157], v[78:79], v[120:121] op_sel_hi:[0,1,1]
	v_cndmask_b32_e64 v94, v94, v158, s[6:7]
	ds_read_b128 v[64:67], v154 offset:36096
	ds_read_b128 v[68:71], v154 offset:36112
	ds_read_b128 v[56:59], v154 offset:35840
	ds_read_b128 v[60:63], v154 offset:35856
	ds_read_b128 v[72:75], v154 offset:36352
	ds_read_b128 v[76:79], v154 offset:36368
	ds_read_b128 v[48:51], v154 offset:35584
	ds_read_b128 v[52:55], v154 offset:35600
	s_waitcnt lgkmcnt(8)
; #define LAS __attribute__((address_space(3)))
; DI unsigned pack2(float lo, float hi) { f32x2 v = {lo, hi}; return __builtin_bit_cast(unsigned, __builtin_convertvector(v, bf16x2_t)); }
; DI void scan_item(PP p, int l, int item, LAS unsigned char* lds) {
;     ...
;     for (int c = 0; c < NCH; ++c) {
;         if (wid >= 4) { if (c + 1 < NCH) { fill(c + 1); if (c + 2 < NCH) gl(c + 2); } }
;         else {
;             const LAS float* sp = buf + ((c & 1) * T) * 384;
;             f32x4 Ar0, Ar1, Aw0, Aw1, Ak0, Ak1, Aa0, Aa1, Ab0, Ab1; float Avv;
;             f32x4 Br0, Br1, Bw0, Bw1, Bk0, Bk1, Ba0, Ba1, Bb0, Bb1; float Bvv;
;             SC_LD(A, sp);
;             const ptrdiff_t ystep = dir ? -512 : 512;
;             u16* Yl = Yp + (size_t)steprow(b, dir, c * T) * 512 + (ptrdiff_t)ks * ystep;
; #pragma nounroll
;             for (int st = 0; st < T; st += 2) {
;                 SC_LD(B, sp + (st + 1) * 384);
;                 SC_STEP(A, st);
;                 if (st + 2 < T) SC_LD(A, sp + (st + 2) * 384);
;                 SC_STEP(B, st + 1);
;                 if ((st & 6) == 6) {
;                     const LAS float* rp = ypl + (ks * 68 - lane) + (lane & ~7);
;                     const f32x4 q0 = *(const LAS f32x4*)rp, q1 = *(const LAS f32x4*)(rp + 4);
;                     Yl[(ptrdiff_t)(st - 6) * ystep] = (u16)(pack2(((q0[0] + q0[1]) + (q0[2] + q0[3])) + ((q1[0] + q1[1]) + (q1[2] + q1[3])), 0.f) & 0xffffu);
;                 }
	v_pk_mul_f32 v[156:157], v[24:25], v[126:127]
	v_pk_mul_f32 v[90:91], v[28:29], v[122:123]
	v_pk_mul_f32 v[158:159], v[40:41], v[126:127]
	v_pk_fma_f32 v[156:157], v[124:125], v[26:27], v[156:157]
	v_pk_fma_f32 v[90:91], v[120:121], v[30:31], v[90:91]
	v_pk_fma_f32 v[158:159], v[124:125], v[42:43], v[158:159]
	v_pk_fma_f32 v[126:127], v[98:99], v[16:17], v[126:127] op_sel_hi:[0,1,1]
	v_pk_fma_f32 v[158:159], v[122:123], v[44:45], v[158:159]
	v_pk_fma_f32 v[124:125], v[98:99], v[18:19], v[124:125] op_sel_hi:[0,1,1]
	v_pk_add_f32 v[156:157], v[156:157], v[90:91]
	v_pk_fma_f32 v[158:159], v[120:121], v[46:47], v[158:159]
	v_add_f32_e32 v155, v156, v157
	v_pk_fma_f32 v[122:123], v[98:99], v[20:21], v[122:123] op_sel_hi:[0,1,1]
	v_pk_fma_f32 v[120:121], v[98:99], v[22:23], v[120:121] op_sel_hi:[0,1,1]
	ds_read_b128 v[40:43], v154 offset:35328
	ds_read_b128 v[44:47], v154 offset:35344
	v_add_f32_e32 v158, v158, v159
	v_add_f32_dpp v155, v155, v155 quad_perm:[1,0,3,2] row_mask:0xf bank_mask:0xf bound_ctrl:1
	s_mov_b32 s6, 0x20202020
	s_mov_b32 s7, 0x20202020
	v_add_f32_dpp v158, v158, v158 quad_perm:[1,0,3,2] row_mask:0xf bank_mask:0xf bound_ctrl:1
	v_add_f32_dpp v155, v155, v155 quad_perm:[2,3,0,1] row_mask:0xf bank_mask:0xf bound_ctrl:1
	s_nop 0
	v_add_f32_dpp v158, v158, v158 quad_perm:[2,3,0,1] row_mask:0xf bank_mask:0xf bound_ctrl:1
	v_add_f32_dpp v156, v155, v155 row_half_mirror row_mask:0xf bank_mask:0xf bound_ctrl:1
	v_pk_fma_f32 v[126:127], v[156:157], v[32:33], v[126:127] op_sel_hi:[0,1,1]
	v_pk_fma_f32 v[124:125], v[156:157], v[34:35], v[124:125] op_sel_hi:[0,1,1]
	v_add_f32_dpp v158, v158, v158 row_half_mirror row_mask:0xf bank_mask:0xf bound_ctrl:1
	v_pk_fma_f32 v[122:123], v[156:157], v[36:37], v[122:123] op_sel_hi:[0,1,1]
	v_pk_fma_f32 v[120:121], v[156:157], v[38:39], v[120:121] op_sel_hi:[0,1,1]
	v_cndmask_b32_e64 v94, v94, v158, s[6:7]
	ds_read_b128 v[24:27], v154 offset:37632
	ds_read_b128 v[28:31], v154 offset:37648
	ds_read_b128 v[16:19], v154 offset:37376
	ds_read_b128 v[20:23], v154 offset:37392
	ds_read_b128 v[32:35], v154 offset:37888
	ds_read_b128 v[36:39], v154 offset:37904
	ds_read2st64_b32 v[92:93], v153 offset0:149 offset1:155
	s_waitcnt lgkmcnt(7)
	v_pk_mul_f32 v[156:157], v[64:65], v[126:127]
	v_pk_mul_f32 v[90:91], v[68:69], v[122:123]
	v_pk_mul_f32 v[158:159], v[0:1], v[126:127]
	v_pk_fma_f32 v[156:157], v[124:125], v[66:67], v[156:157]
	v_pk_fma_f32 v[90:91], v[120:121], v[70:71], v[90:91]
	v_pk_fma_f32 v[158:159], v[124:125], v[2:3], v[158:159]
	v_pk_fma_f32 v[126:127], v[98:99], v[56:57], v[126:127] op_sel:[1,0,0] op_sel_hi:[1,1,1]
	v_pk_fma_f32 v[158:159], v[122:123], v[4:5], v[158:159]
	v_pk_fma_f32 v[124:125], v[98:99], v[58:59], v[124:125] op_sel:[1,0,0] op_sel_hi:[1,1,1]
	v_pk_add_f32 v[156:157], v[156:157], v[90:91]
	v_pk_fma_f32 v[158:159], v[120:121], v[6:7], v[158:159]
	v_add_f32_e32 v155, v156, v157
	v_pk_fma_f32 v[122:123], v[98:99], v[60:61], v[122:123] op_sel:[1,0,0] op_sel_hi:[1,1,1]
	v_pk_fma_f32 v[120:121], v[98:99], v[62:63], v[120:121] op_sel:[1,0,0] op_sel_hi:[1,1,1]
	ds_read_b128 v[0:3], v154 offset:36864
	ds_read_b128 v[4:7], v154 offset:36880
	v_add_f32_e32 v158, v158, v159
	v_add_f32_dpp v155, v155, v155 quad_perm:[1,0,3,2] row_mask:0xf bank_mask:0xf bound_ctrl:1
	s_mov_b32 s6, 0x40404040
	s_mov_b32 s7, 0x40404040
	v_add_f32_dpp v158, v158, v158 quad_perm:[1,0,3,2] row_mask:0xf bank_mask:0xf bound_ctrl:1
	v_add_f32_dpp v155, v155, v155 quad_perm:[2,3,0,1] row_mask:0xf bank_mask:0xf bound_ctrl:1
	s_nop 0
	v_add_f32_dpp v158, v158, v158 quad_perm:[2,3,0,1] row_mask:0xf bank_mask:0xf bound_ctrl:1
	v_add_f32_dpp v156, v155, v155 row_half_mirror row_mask:0xf bank_mask:0xf bound_ctrl:1
	v_pk_fma_f32 v[126:127], v[156:157], v[72:73], v[126:127] op_sel_hi:[0,1,1]
	v_pk_fma_f32 v[124:125], v[156:157], v[74:75], v[124:125] op_sel_hi:[0,1,1]
	v_add_f32_dpp v158, v158, v158 row_half_mirror row_mask:0xf bank_mask:0xf bound_ctrl:1
	v_pk_fma_f32 v[122:123], v[156:157], v[76:77], v[122:123] op_sel_hi:[0,1,1]
	v_pk_fma_f32 v[120:121], v[156:157], v[78:79], v[120:121] op_sel_hi:[0,1,1]
	v_cndmask_b32_e64 v94, v94, v158, s[6:7]
	v_pk_mul_f32 v[158:159], v[40:41], v[126:127]
	v_pk_mul_f32 v[126:127], v[48:49], v[126:127]
	v_pk_fma_f32 v[158:159], v[124:125], v[42:43], v[158:159]
	v_pk_mul_f32 v[124:125], v[50:51], v[124:125]
	v_pk_fma_f32 v[158:159], v[122:123], v[44:45], v[158:159]
	v_pk_mul_f32 v[122:123], v[52:53], v[122:123]
	v_pk_fma_f32 v[158:159], v[120:121], v[46:47], v[158:159]
	v_pk_mul_f32 v[120:121], v[54:55], v[120:121]
	v_add_f32_e32 v158, v158, v159
	s_mov_b32 s6, 0x80808080
	s_mov_b32 s7, 0x80808080
	v_add_f32_dpp v158, v158, v158 quad_perm:[1,0,3,2] row_mask:0xf bank_mask:0xf bound_ctrl:1
	s_nop 1
	v_add_f32_dpp v158, v158, v158 quad_perm:[2,3,0,1] row_mask:0xf bank_mask:0xf bound_ctrl:1
	s_nop 1
	v_add_f32_dpp v158, v158, v158 row_half_mirror row_mask:0xf bank_mask:0xf bound_ctrl:1
	v_cndmask_b32_e64 v94, v94, v158, s[6:7]
	ds_read_b128 v[40:43], v154 offset:38400
	ds_read_b128 v[44:47], v154 offset:38416
	ds_read_b128 v[64:67], v154 offset:39168
	ds_read_b128 v[68:71], v154 offset:39184
	ds_read_b128 v[56:59], v154 offset:38912
	ds_read_b128 v[60:63], v154 offset:38928
	ds_read_b128 v[72:75], v154 offset:39424
	ds_read_b128 v[76:79], v154 offset:39440
	s_waitcnt lgkmcnt(8)
; #define LAS __attribute__((address_space(3)))
; DI unsigned pack2(float lo, float hi) { f32x2 v = {lo, hi}; return __builtin_bit_cast(unsigned, __builtin_convertvector(v, bf16x2_t)); }
; DI void scan_item(PP p, int l, int item, LAS unsigned char* lds) {
;     ...
;     for (int c = 0; c < NCH; ++c) {
;         if (wid >= 4) { if (c + 1 < NCH) { fill(c + 1); if (c + 2 < NCH) gl(c + 2); } }
;         else {
;             const LAS float* sp = buf + ((c & 1) * T) * 384;
;             f32x4 Ar0, Ar1, Aw0, Aw1, Ak0, Ak1, Aa0, Aa1, Ab0, Ab1; float Avv;
;             f32x4 Br0, Br1, Bw0, Bw1, Bk0, Bk1, Ba0, Ba1, Bb0, Bb1; float Bvv;
;             SC_LD(A, sp);
;             const ptrdiff_t ystep = dir ? -512 : 512;
;             u16* Yl = Yp + (size_t)steprow(b, dir, c * T) * 512 + (ptrdiff_t)ks * ystep;
; #pragma nounroll
;             for (int st = 0; st < T; st += 2) {
;                 SC_LD(B, sp + (st + 1) * 384);
;                 SC_STEP(A, st);
;                 if (st + 2 < T) SC_LD(A, sp + (st + 2) * 384);
;                 SC_STEP(B, st + 1);
;                 if ((st & 6) == 6) {
;                     const LAS float* rp = ypl + (ks * 68 - lane) + (lane & ~7);
;                     const f32x4 q0 = *(const LAS f32x4*)rp, q1 = *(const LAS f32x4*)(rp + 4);
;                     Yl[(ptrdiff_t)(st - 6) * ystep] = (u16)(pack2(((q0[0] + q0[1]) + (q0[2] + q0[3])) + ((q1[0] + q1[1]) + (q1[2] + q1[3])), 0.f) & 0xffffu);
;                 }
	v_pk_mul_f32 v[156:157], v[24:25], v[126:127]
	v_pk_mul_f32 v[90:91], v[28:29], v[122:123]
	v_pk_fma_f32 v[126:127], v[92:93], v[16:17], v[126:127] op_sel_hi:[0,1,1]
	v_pk_fma_f32 v[156:157], v[124:125], v[26:27], v[156:157]
	v_pk_fma_f32 v[90:91], v[120:121], v[30:31], v[90:91]
	v_pk_fma_f32 v[124:125], v[92:93], v[18:19], v[124:125] op_sel_hi:[0,1,1]
	v_pk_fma_f32 v[122:123], v[92:93], v[20:21], v[122:123] op_sel_hi:[0,1,1]
	v_pk_add_f32 v[156:157], v[156:157], v[90:91]
	v_pk_fma_f32 v[120:121], v[92:93], v[22:23], v[120:121] op_sel_hi:[0,1,1]
	v_add_f32_e32 v155, v156, v157
	s_nop 1
	v_add_f32_dpp v155, v155, v155 quad_perm:[1,0,3,2] row_mask:0xf bank_mask:0xf bound_ctrl:1
	s_nop 1
	v_add_f32_dpp v155, v155, v155 quad_perm:[2,3,0,1] row_mask:0xf bank_mask:0xf bound_ctrl:1
	s_nop 1
	v_add_f32_dpp v156, v155, v155 row_half_mirror row_mask:0xf bank_mask:0xf bound_ctrl:1
	v_pk_fma_f32 v[126:127], v[156:157], v[32:33], v[126:127] op_sel_hi:[0,1,1]
	v_pk_fma_f32 v[124:125], v[156:157], v[34:35], v[124:125] op_sel_hi:[0,1,1]
	v_pk_fma_f32 v[122:123], v[156:157], v[36:37], v[122:123] op_sel_hi:[0,1,1]
	v_pk_fma_f32 v[120:121], v[156:157], v[38:39], v[120:121] op_sel_hi:[0,1,1]
	v_cvt_pk_bf16_f32 v82, v94, v94
	global_store_short v[118:119], v82, off
	v_lshl_add_u64 v[118:119], s[8:9], 0, v[118:119]
	ds_read_b128 v[24:27], v154 offset:40704
	ds_read_b128 v[28:31], v154 offset:40720
	ds_read_b128 v[16:19], v154 offset:40448
	ds_read_b128 v[20:23], v154 offset:40464
	ds_read_b128 v[32:35], v154 offset:40960
	ds_read_b128 v[36:39], v154 offset:40976
	ds_read2st64_b32 v[98:99], v153 offset0:161 offset1:167
	s_waitcnt lgkmcnt(7)
	v_pk_mul_f32 v[156:157], v[64:65], v[126:127]
	v_pk_mul_f32 v[90:91], v[68:69], v[122:123]
	v_pk_mul_f32 v[158:159], v[0:1], v[126:127]
	v_pk_fma_f32 v[156:157], v[124:125], v[66:67], v[156:157]
	v_pk_fma_f32 v[90:91], v[120:121], v[70:71], v[90:91]
	v_pk_fma_f32 v[158:159], v[124:125], v[2:3], v[158:159]
	v_pk_fma_f32 v[126:127], v[92:93], v[56:57], v[126:127] op_sel:[1,0,0] op_sel_hi:[1,1,1]
	v_pk_fma_f32 v[158:159], v[122:123], v[4:5], v[158:159]
	v_pk_fma_f32 v[124:125], v[92:93], v[58:59], v[124:125] op_sel:[1,0,0] op_sel_hi:[1,1,1]
	v_pk_add_f32 v[156:157], v[156:157], v[90:91]
	v_pk_fma_f32 v[158:159], v[120:121], v[6:7], v[158:159]
	v_add_f32_e32 v155, v156, v157
	v_pk_fma_f32 v[122:123], v[92:93], v[60:61], v[122:123] op_sel:[1,0,0] op_sel_hi:[1,1,1]
	v_pk_fma_f32 v[120:121], v[92:93], v[62:63], v[120:121] op_sel:[1,0,0] op_sel_hi:[1,1,1]
	ds_read_b128 v[0:3], v154 offset:39936
	ds_read_b128 v[4:7], v154 offset:39952
	v_add_f32_e32 v158, v158, v159
	v_add_f32_dpp v155, v155, v155 quad_perm:[1,0,3,2] row_mask:0xf bank_mask:0xf bound_ctrl:1
	s_mov_b32 s6, 0x1010101
	s_mov_b32 s7, 0x1010101
	v_add_f32_dpp v158, v158, v158 quad_perm:[1,0,3,2] row_mask:0xf bank_mask:0xf bound_ctrl:1
	v_add_f32_dpp v155, v155, v155 quad_perm:[2,3,0,1] row_mask:0xf bank_mask:0xf bound_ctrl:1
	s_nop 0
	v_add_f32_dpp v158, v158, v158 quad_perm:[2,3,0,1] row_mask:0xf bank_mask:0xf bound_ctrl:1
	v_add_f32_dpp v156, v155, v155 row_half_mirror row_mask:0xf bank_mask:0xf bound_ctrl:1
	v_pk_fma_f32 v[126:127], v[156:157], v[72:73], v[126:127] op_sel_hi:[0,1,1]
	v_pk_fma_f32 v[124:125], v[156:157], v[74:75], v[124:125] op_sel_hi:[0,1,1]
	v_add_f32_dpp v158, v158, v158 row_half_mirror row_mask:0xf bank_mask:0xf bound_ctrl:1
	v_pk_fma_f32 v[122:123], v[156:157], v[76:77], v[122:123] op_sel_hi:[0,1,1]
	v_pk_fma_f32 v[120:121], v[156:157], v[78:79], v[120:121] op_sel_hi:[0,1,1]
	v_cndmask_b32_e64 v94, v94, v158, s[6:7]
	ds_read_b128 v[64:67], v154 offset:42240
	ds_read_b128 v[68:71], v154 offset:42256
	ds_read_b128 v[56:59], v154 offset:41984
	ds_read_b128 v[60:63], v154 offset:42000
	ds_read_b128 v[72:75], v154 offset:42496
	ds_read_b128 v[76:79], v154 offset:42512
	s_waitcnt lgkmcnt(6)
	v_pk_mul_f32 v[156:157], v[24:25], v[126:127]
	v_pk_mul_f32 v[90:91], v[28:29], v[122:123]
	v_pk_mul_f32 v[158:159], v[40:41], v[126:127]
	v_pk_fma_f32 v[156:157], v[124:125], v[26:27], v[156:157]
	v_pk_fma_f32 v[90:91], v[120:121], v[30:31], v[90:91]
	v_pk_fma_f32 v[158:159], v[124:125], v[42:43], v[158:159]
	v_pk_fma_f32 v[126:127], v[98:99], v[16:17], v[126:127] op_sel_hi:[0,1,1]
	v_pk_fma_f32 v[158:159], v[122:123], v[44:45], v[158:159]
	v_pk_fma_f32 v[124:125], v[98:99], v[18:19], v[124:125] op_sel_hi:[0,1,1]
	v_pk_add_f32 v[156:157], v[156:157], v[90:91]
	v_pk_fma_f32 v[158:159], v[120:121], v[46:47], v[158:159]
	v_add_f32_e32 v155, v156, v157
	v_pk_fma_f32 v[122:123], v[98:99], v[20:21], v[122:123] op_sel_hi:[0,1,1]
	v_pk_fma_f32 v[120:121], v[98:99], v[22:23], v[120:121] op_sel_hi:[0,1,1]
	ds_read_b128 v[40:43], v154 offset:41472
	ds_read_b128 v[44:47], v154 offset:41488
	v_add_f32_e32 v158, v158, v159
	v_add_f32_dpp v155, v155, v155 quad_perm:[1,0,3,2] row_mask:0xf bank_mask:0xf bound_ctrl:1
	s_mov_b32 s6, 0x2020202
	s_mov_b32 s7, 0x2020202
	v_add_f32_dpp v158, v158, v158 quad_perm:[1,0,3,2] row_mask:0xf bank_mask:0xf bound_ctrl:1
	v_add_f32_dpp v155, v155, v155 quad_perm:[2,3,0,1] row_mask:0xf bank_mask:0xf bound_ctrl:1
	s_nop 0
	v_add_f32_dpp v158, v158, v158 quad_perm:[2,3,0,1] row_mask:0xf bank_mask:0xf bound_ctrl:1
	v_add_f32_dpp v156, v155, v155 row_half_mirror row_mask:0xf bank_mask:0xf bound_ctrl:1
	v_pk_fma_f32 v[126:127], v[156:157], v[32:33], v[126:127] op_sel_hi:[0,1,1]
	v_pk_fma_f32 v[124:125], v[156:157], v[34:35], v[124:125] op_sel_hi:[0,1,1]
	v_add_f32_dpp v158, v158, v158 row_half_mirror row_mask:0xf bank_mask:0xf bound_ctrl:1
	v_pk_fma_f32 v[122:123], v[156:157], v[36:37], v[122:123] op_sel_hi:[0,1,1]
	v_pk_fma_f32 v[120:121], v[156:157], v[38:39], v[120:121] op_sel_hi:[0,1,1]
	v_cndmask_b32_e64 v94, v94, v158, s[6:7]
	ds_read_b128 v[24:27], v154 offset:43776
	ds_read_b128 v[28:31], v154 offset:43792
	ds_read_b128 v[16:19], v154 offset:43520
	ds_read_b128 v[20:23], v154 offset:43536
	ds_read_b128 v[32:35], v154 offset:44032
	ds_read_b128 v[36:39], v154 offset:44048
	ds_read2st64_b32 v[92:93], v153 offset0:173 offset1:179
	s_waitcnt lgkmcnt(7)
; #define LAS __attribute__((address_space(3)))
; DI unsigned pack2(float lo, float hi) { f32x2 v = {lo, hi}; return __builtin_bit_cast(unsigned, __builtin_convertvector(v, bf16x2_t)); }
; DI void scan_item(PP p, int l, int item, LAS unsigned char* lds) {
;     ...
;     for (int c = 0; c < NCH; ++c) {
;         if (wid >= 4) { if (c + 1 < NCH) { fill(c + 1); if (c + 2 < NCH) gl(c + 2); } }
;         else {
;             const LAS float* sp = buf + ((c & 1) * T) * 384;
;             f32x4 Ar0, Ar1, Aw0, Aw1, Ak0, Ak1, Aa0, Aa1, Ab0, Ab1; float Avv;
;             f32x4 Br0, Br1, Bw0, Bw1, Bk0, Bk1, Ba0, Ba1, Bb0, Bb1; float Bvv;
;             SC_LD(A, sp);
;             const ptrdiff_t ystep = dir ? -512 : 512;
;             u16* Yl = Yp + (size_t)steprow(b, dir, c * T) * 512 + (ptrdiff_t)ks * ystep;
; #pragma nounroll
;             for (int st = 0; st < T; st += 2) {
;                 SC_LD(B, sp + (st + 1) * 384);
;                 SC_STEP(A, st);
;                 if (st + 2 < T) SC_LD(A, sp + (st + 2) * 384);
;                 SC_STEP(B, st + 1);
;                 if ((st & 6) == 6) {
;                     const LAS float* rp = ypl + (ks * 68 - lane) + (lane & ~7);
;                     const f32x4 q0 = *(const LAS f32x4*)rp, q1 = *(const LAS f32x4*)(rp + 4);
;                     Yl[(ptrdiff_t)(st - 6) * ystep] = (u16)(pack2(((q0[0] + q0[1]) + (q0[2] + q0[3])) + ((q1[0] + q1[1]) + (q1[2] + q1[3])), 0.f) & 0xffffu);
;                 }
	v_pk_mul_f32 v[156:157], v[64:65], v[126:127]
	v_pk_mul_f32 v[90:91], v[68:69], v[122:123]
	v_pk_mul_f32 v[158:159], v[0:1], v[126:127]
	v_pk_fma_f32 v[156:157], v[124:125], v[66:67], v[156:157]
	v_pk_fma_f32 v[90:91], v[120:121], v[70:71], v[90:91]
	v_pk_fma_f32 v[158:159], v[124:125], v[2:3], v[158:159]
	v_pk_fma_f32 v[126:127], v[98:99], v[56:57], v[126:127] op_sel:[1,0,0] op_sel_hi:[1,1,1]
	v_pk_fma_f32 v[158:159], v[122:123], v[4:5], v[158:159]
	v_pk_fma_f32 v[124:125], v[98:99], v[58:59], v[124:125] op_sel:[1,0,0] op_sel_hi:[1,1,1]
	v_pk_add_f32 v[156:157], v[156:157], v[90:91]
	v_pk_fma_f32 v[158:159], v[120:121], v[6:7], v[158:159]
	v_add_f32_e32 v155, v156, v157
	v_pk_fma_f32 v[122:123], v[98:99], v[60:61], v[122:123] op_sel:[1,0,0] op_sel_hi:[1,1,1]
	v_pk_fma_f32 v[120:121], v[98:99], v[62:63], v[120:121] op_sel:[1,0,0] op_sel_hi:[1,1,1]
	ds_read_b128 v[0:3], v154 offset:43008
	ds_read_b128 v[4:7], v154 offset:43024
	v_add_f32_e32 v158, v158, v159
	v_add_f32_dpp v155, v155, v155 quad_perm:[1,0,3,2] row_mask:0xf bank_mask:0xf bound_ctrl:1
	s_mov_b32 s6, 0x4040404
	s_mov_b32 s7, 0x4040404
	v_add_f32_dpp v158, v158, v158 quad_perm:[1,0,3,2] row_mask:0xf bank_mask:0xf bound_ctrl:1
	v_add_f32_dpp v155, v155, v155 quad_perm:[2,3,0,1] row_mask:0xf bank_mask:0xf bound_ctrl:1
	s_nop 0
	v_add_f32_dpp v158, v158, v158 quad_perm:[2,3,0,1] row_mask:0xf bank_mask:0xf bound_ctrl:1
	v_add_f32_dpp v156, v155, v155 row_half_mirror row_mask:0xf bank_mask:0xf bound_ctrl:1
	v_pk_fma_f32 v[126:127], v[156:157], v[72:73], v[126:127] op_sel_hi:[0,1,1]
	v_pk_fma_f32 v[124:125], v[156:157], v[74:75], v[124:125] op_sel_hi:[0,1,1]
	v_add_f32_dpp v158, v158, v158 row_half_mirror row_mask:0xf bank_mask:0xf bound_ctrl:1
	v_pk_fma_f32 v[122:123], v[156:157], v[76:77], v[122:123] op_sel_hi:[0,1,1]
	v_pk_fma_f32 v[120:121], v[156:157], v[78:79], v[120:121] op_sel_hi:[0,1,1]
	v_cndmask_b32_e64 v94, v94, v158, s[6:7]
	ds_read_b128 v[64:67], v154 offset:45312
	ds_read_b128 v[68:71], v154 offset:45328
	ds_read_b128 v[56:59], v154 offset:45056
	ds_read_b128 v[60:63], v154 offset:45072
	ds_read_b128 v[72:75], v154 offset:45568
	ds_read_b128 v[76:79], v154 offset:45584
	s_waitcnt lgkmcnt(6)
	v_pk_mul_f32 v[156:157], v[24:25], v[126:127]
	v_pk_mul_f32 v[90:91], v[28:29], v[122:123]
	v_pk_mul_f32 v[158:159], v[40:41], v[126:127]
	v_pk_fma_f32 v[156:157], v[124:125], v[26:27], v[156:157]
	v_pk_fma_f32 v[90:91], v[120:121], v[30:31], v[90:91]
	v_pk_fma_f32 v[158:159], v[124:125], v[42:43], v[158:159]
	v_pk_fma_f32 v[126:127], v[92:93], v[16:17], v[126:127] op_sel_hi:[0,1,1]
	v_pk_fma_f32 v[158:159], v[122:123], v[44:45], v[158:159]
	v_pk_fma_f32 v[124:125], v[92:93], v[18:19], v[124:125] op_sel_hi:[0,1,1]
	v_pk_add_f32 v[156:157], v[156:157], v[90:91]
	v_pk_fma_f32 v[158:159], v[120:121], v[46:47], v[158:159]
	v_add_f32_e32 v155, v156, v157
	v_pk_fma_f32 v[122:123], v[92:93], v[20:21], v[122:123] op_sel_hi:[0,1,1]
	v_pk_fma_f32 v[120:121], v[92:93], v[22:23], v[120:121] op_sel_hi:[0,1,1]
	ds_read_b128 v[40:43], v154 offset:44544
	ds_read_b128 v[44:47], v154 offset:44560
	v_add_f32_e32 v158, v158, v159
	v_add_f32_dpp v155, v155, v155 quad_perm:[1,0,3,2] row_mask:0xf bank_mask:0xf bound_ctrl:1
	s_mov_b32 s6, 0x8080808
	s_mov_b32 s7, 0x8080808
	v_add_f32_dpp v158, v158, v158 quad_perm:[1,0,3,2] row_mask:0xf bank_mask:0xf bound_ctrl:1
	v_add_f32_dpp v155, v155, v155 quad_perm:[2,3,0,1] row_mask:0xf bank_mask:0xf bound_ctrl:1
	s_nop 0
	v_add_f32_dpp v158, v158, v158 quad_perm:[2,3,0,1] row_mask:0xf bank_mask:0xf bound_ctrl:1
	v_add_f32_dpp v156, v155, v155 row_half_mirror row_mask:0xf bank_mask:0xf bound_ctrl:1
	v_pk_fma_f32 v[126:127], v[156:157], v[32:33], v[126:127] op_sel_hi:[0,1,1]
	v_pk_fma_f32 v[124:125], v[156:157], v[34:35], v[124:125] op_sel_hi:[0,1,1]
	v_add_f32_dpp v158, v158, v158 row_half_mirror row_mask:0xf bank_mask:0xf bound_ctrl:1
	v_pk_fma_f32 v[122:123], v[156:157], v[36:37], v[122:123] op_sel_hi:[0,1,1]
	v_pk_fma_f32 v[120:121], v[156:157], v[38:39], v[120:121] op_sel_hi:[0,1,1]
	v_cndmask_b32_e64 v94, v94, v158, s[6:7]
	ds_read_b128 v[24:27], v154 offset:46848
	ds_read_b128 v[28:31], v154 offset:46864
	ds_read_b128 v[16:19], v154 offset:46592
	ds_read_b128 v[20:23], v154 offset:46608
	ds_read_b128 v[32:35], v154 offset:47104
	ds_read_b128 v[36:39], v154 offset:47120
	ds_read2st64_b32 v[98:99], v153 offset0:185 offset1:191
	s_waitcnt lgkmcnt(7)
	v_pk_mul_f32 v[156:157], v[64:65], v[126:127]
	v_pk_mul_f32 v[90:91], v[68:69], v[122:123]
	v_pk_mul_f32 v[158:159], v[0:1], v[126:127]
	v_pk_fma_f32 v[156:157], v[124:125], v[66:67], v[156:157]
	v_pk_fma_f32 v[90:91], v[120:121], v[70:71], v[90:91]
	v_pk_fma_f32 v[158:159], v[124:125], v[2:3], v[158:159]
	v_pk_fma_f32 v[126:127], v[92:93], v[56:57], v[126:127] op_sel:[1,0,0] op_sel_hi:[1,1,1]
	v_pk_fma_f32 v[158:159], v[122:123], v[4:5], v[158:159]
	v_pk_fma_f32 v[124:125], v[92:93], v[58:59], v[124:125] op_sel:[1,0,0] op_sel_hi:[1,1,1]
	v_pk_add_f32 v[156:157], v[156:157], v[90:91]
	v_pk_fma_f32 v[158:159], v[120:121], v[6:7], v[158:159]
	v_add_f32_e32 v155, v156, v157
	v_pk_fma_f32 v[122:123], v[92:93], v[60:61], v[122:123] op_sel:[1,0,0] op_sel_hi:[1,1,1]
	v_pk_fma_f32 v[120:121], v[92:93], v[62:63], v[120:121] op_sel:[1,0,0] op_sel_hi:[1,1,1]
	ds_read_b128 v[0:3], v154 offset:46080
	ds_read_b128 v[4:7], v154 offset:46096
	v_add_f32_e32 v158, v158, v159
	v_add_f32_dpp v155, v155, v155 quad_perm:[1,0,3,2] row_mask:0xf bank_mask:0xf bound_ctrl:1
	s_mov_b32 s6, 0x10101010
	s_mov_b32 s7, 0x10101010
	v_add_f32_dpp v158, v158, v158 quad_perm:[1,0,3,2] row_mask:0xf bank_mask:0xf bound_ctrl:1
	v_add_f32_dpp v155, v155, v155 quad_perm:[2,3,0,1] row_mask:0xf bank_mask:0xf bound_ctrl:1
	s_nop 0
	v_add_f32_dpp v158, v158, v158 quad_perm:[2,3,0,1] row_mask:0xf bank_mask:0xf bound_ctrl:1
	v_add_f32_dpp v156, v155, v155 row_half_mirror row_mask:0xf bank_mask:0xf bound_ctrl:1
	v_pk_fma_f32 v[126:127], v[156:157], v[72:73], v[126:127] op_sel_hi:[0,1,1]
	v_pk_fma_f32 v[124:125], v[156:157], v[74:75], v[124:125] op_sel_hi:[0,1,1]
	v_add_f32_dpp v158, v158, v158 row_half_mirror row_mask:0xf bank_mask:0xf bound_ctrl:1
	v_pk_fma_f32 v[122:123], v[156:157], v[76:77], v[122:123] op_sel_hi:[0,1,1]
	v_pk_fma_f32 v[120:121], v[156:157], v[78:79], v[120:121] op_sel_hi:[0,1,1]
	v_cndmask_b32_e64 v94, v94, v158, s[6:7]
	ds_read_b128 v[64:67], v154 offset:48384
	ds_read_b128 v[68:71], v154 offset:48400
	ds_read_b128 v[56:59], v154 offset:48128
	ds_read_b128 v[60:63], v154 offset:48144
	ds_read_b128 v[72:75], v154 offset:48640
	ds_read_b128 v[76:79], v154 offset:48656
	ds_read_b128 v[48:51], v154 offset:47872
	ds_read_b128 v[52:55], v154 offset:47888
	s_waitcnt lgkmcnt(8)
; #define LAS __attribute__((address_space(3)))
; DI unsigned pack2(float lo, float hi) { f32x2 v = {lo, hi}; return __builtin_bit_cast(unsigned, __builtin_convertvector(v, bf16x2_t)); }
; DI void scan_item(PP p, int l, int item, LAS unsigned char* lds) {
;     ...
;     for (int c = 0; c < NCH; ++c) {
;         if (wid >= 4) { if (c + 1 < NCH) { fill(c + 1); if (c + 2 < NCH) gl(c + 2); } }
;         else {
;             const LAS float* sp = buf + ((c & 1) * T) * 384;
;             f32x4 Ar0, Ar1, Aw0, Aw1, Ak0, Ak1, Aa0, Aa1, Ab0, Ab1; float Avv;
;             f32x4 Br0, Br1, Bw0, Bw1, Bk0, Bk1, Ba0, Ba1, Bb0, Bb1; float Bvv;
;             SC_LD(A, sp);
;             const ptrdiff_t ystep = dir ? -512 : 512;
;             u16* Yl = Yp + (size_t)steprow(b, dir, c * T) * 512 + (ptrdiff_t)ks * ystep;
; #pragma nounroll
;             for (int st = 0; st < T; st += 2) {
;                 SC_LD(B, sp + (st + 1) * 384);
;                 SC_STEP(A, st);
;                 if (st + 2 < T) SC_LD(A, sp + (st + 2) * 384);
;                 SC_STEP(B, st + 1);
;                 if ((st & 6) == 6) {
;                     const LAS float* rp = ypl + (ks * 68 - lane) + (lane & ~7);
;                     const f32x4 q0 = *(const LAS f32x4*)rp, q1 = *(const LAS f32x4*)(rp + 4);
;                     Yl[(ptrdiff_t)(st - 6) * ystep] = (u16)(pack2(((q0[0] + q0[1]) + (q0[2] + q0[3])) + ((q1[0] + q1[1]) + (q1[2] + q1[3])), 0.f) & 0xffffu);
;                 }
	v_pk_mul_f32 v[156:157], v[24:25], v[126:127]
	v_pk_mul_f32 v[90:91], v[28:29], v[122:123]
	v_pk_mul_f32 v[158:159], v[40:41], v[126:127]
	v_pk_fma_f32 v[156:157], v[124:125], v[26:27], v[156:157]
	v_pk_fma_f32 v[90:91], v[120:121], v[30:31], v[90:91]
	v_pk_fma_f32 v[158:159], v[124:125], v[42:43], v[158:159]
	v_pk_fma_f32 v[126:127], v[98:99], v[16:17], v[126:127] op_sel_hi:[0,1,1]
	v_pk_fma_f32 v[158:159], v[122:123], v[44:45], v[158:159]
	v_pk_fma_f32 v[124:125], v[98:99], v[18:19], v[124:125] op_sel_hi:[0,1,1]
	v_pk_add_f32 v[156:157], v[156:157], v[90:91]
	v_pk_fma_f32 v[158:159], v[120:121], v[46:47], v[158:159]
	v_add_f32_e32 v155, v156, v157
	v_pk_fma_f32 v[122:123], v[98:99], v[20:21], v[122:123] op_sel_hi:[0,1,1]
	v_pk_fma_f32 v[120:121], v[98:99], v[22:23], v[120:121] op_sel_hi:[0,1,1]
	ds_read_b128 v[40:43], v154 offset:47616
	ds_read_b128 v[44:47], v154 offset:47632
	v_add_f32_e32 v158, v158, v159
	v_add_f32_dpp v155, v155, v155 quad_perm:[1,0,3,2] row_mask:0xf bank_mask:0xf bound_ctrl:1
	s_mov_b32 s6, 0x20202020
	s_mov_b32 s7, 0x20202020
	v_add_f32_dpp v158, v158, v158 quad_perm:[1,0,3,2] row_mask:0xf bank_mask:0xf bound_ctrl:1
	v_add_f32_dpp v155, v155, v155 quad_perm:[2,3,0,1] row_mask:0xf bank_mask:0xf bound_ctrl:1
	s_nop 0
	v_add_f32_dpp v158, v158, v158 quad_perm:[2,3,0,1] row_mask:0xf bank_mask:0xf bound_ctrl:1
	v_add_f32_dpp v156, v155, v155 row_half_mirror row_mask:0xf bank_mask:0xf bound_ctrl:1
	v_pk_fma_f32 v[126:127], v[156:157], v[32:33], v[126:127] op_sel_hi:[0,1,1]
	v_pk_fma_f32 v[124:125], v[156:157], v[34:35], v[124:125] op_sel_hi:[0,1,1]
	v_add_f32_dpp v158, v158, v158 row_half_mirror row_mask:0xf bank_mask:0xf bound_ctrl:1
	v_pk_fma_f32 v[122:123], v[156:157], v[36:37], v[122:123] op_sel_hi:[0,1,1]
	v_pk_fma_f32 v[120:121], v[156:157], v[38:39], v[120:121] op_sel_hi:[0,1,1]
	v_cndmask_b32_e64 v94, v94, v158, s[6:7]
	s_waitcnt lgkmcnt(0)
	v_pk_mul_f32 v[156:157], v[64:65], v[126:127]
	v_pk_mul_f32 v[90:91], v[68:69], v[122:123]
	v_pk_mul_f32 v[158:159], v[0:1], v[126:127]
	v_pk_fma_f32 v[156:157], v[124:125], v[66:67], v[156:157]
	v_pk_fma_f32 v[90:91], v[120:121], v[70:71], v[90:91]
	v_pk_fma_f32 v[158:159], v[124:125], v[2:3], v[158:159]
	v_pk_fma_f32 v[126:127], v[98:99], v[56:57], v[126:127] op_sel:[1,0,0] op_sel_hi:[1,1,1]
	v_pk_fma_f32 v[158:159], v[122:123], v[4:5], v[158:159]
	v_pk_fma_f32 v[124:125], v[98:99], v[58:59], v[124:125] op_sel:[1,0,0] op_sel_hi:[1,1,1]
	v_pk_add_f32 v[156:157], v[156:157], v[90:91]
	v_pk_fma_f32 v[158:159], v[120:121], v[6:7], v[158:159]
	v_add_f32_e32 v155, v156, v157
	v_pk_fma_f32 v[122:123], v[98:99], v[60:61], v[122:123] op_sel:[1,0,0] op_sel_hi:[1,1,1]
	v_pk_fma_f32 v[120:121], v[98:99], v[62:63], v[120:121] op_sel:[1,0,0] op_sel_hi:[1,1,1]
	v_add_f32_e32 v158, v158, v159
	v_add_f32_dpp v155, v155, v155 quad_perm:[1,0,3,2] row_mask:0xf bank_mask:0xf bound_ctrl:1
	s_mov_b32 s6, 0x40404040
	s_mov_b32 s7, 0x40404040
	v_add_f32_dpp v158, v158, v158 quad_perm:[1,0,3,2] row_mask:0xf bank_mask:0xf bound_ctrl:1
	v_add_f32_dpp v155, v155, v155 quad_perm:[2,3,0,1] row_mask:0xf bank_mask:0xf bound_ctrl:1
	s_nop 0
	v_add_f32_dpp v158, v158, v158 quad_perm:[2,3,0,1] row_mask:0xf bank_mask:0xf bound_ctrl:1
	v_add_f32_dpp v156, v155, v155 row_half_mirror row_mask:0xf bank_mask:0xf bound_ctrl:1
	v_pk_fma_f32 v[126:127], v[156:157], v[72:73], v[126:127] op_sel_hi:[0,1,1]
	v_pk_fma_f32 v[124:125], v[156:157], v[74:75], v[124:125] op_sel_hi:[0,1,1]
	v_add_f32_dpp v158, v158, v158 row_half_mirror row_mask:0xf bank_mask:0xf bound_ctrl:1
	v_pk_fma_f32 v[122:123], v[156:157], v[76:77], v[122:123] op_sel_hi:[0,1,1]
	v_pk_fma_f32 v[120:121], v[156:157], v[78:79], v[120:121] op_sel_hi:[0,1,1]
	v_cndmask_b32_e64 v94, v94, v158, s[6:7]
	v_pk_mul_f32 v[158:159], v[40:41], v[126:127]
	v_pk_mul_f32 v[126:127], v[48:49], v[126:127]
	v_pk_fma_f32 v[158:159], v[124:125], v[42:43], v[158:159]
	v_pk_mul_f32 v[124:125], v[50:51], v[124:125]
	v_pk_fma_f32 v[158:159], v[122:123], v[44:45], v[158:159]
	v_pk_mul_f32 v[122:123], v[52:53], v[122:123]
	v_pk_fma_f32 v[158:159], v[120:121], v[46:47], v[158:159]
	v_pk_mul_f32 v[120:121], v[54:55], v[120:121]
	v_add_f32_e32 v158, v158, v159
	s_mov_b32 s6, 0x80808080
	s_mov_b32 s7, 0x80808080
	v_add_f32_dpp v158, v158, v158 quad_perm:[1,0,3,2] row_mask:0xf bank_mask:0xf bound_ctrl:1
	s_nop 1
	v_add_f32_dpp v158, v158, v158 quad_perm:[2,3,0,1] row_mask:0xf bank_mask:0xf bound_ctrl:1
	s_nop 1
	v_add_f32_dpp v158, v158, v158 row_half_mirror row_mask:0xf bank_mask:0xf bound_ctrl:1
	v_cndmask_b32_e64 v94, v94, v158, s[6:7]
	v_cvt_pk_bf16_f32 v82, v94, v94
	global_store_short v[118:119], v82, off
	s_setprio 0
